# stack: + bf16 norm loops of phases 5/10/13 unrolled with all 8 rows' loads issued up front
# speedup vs baseline: 1.0078x; 1.0007x over previous
.LBB0_495:
	v_lshrrev_b32_e32 v16, 8, v93
	v_mul_hi_i32_i24_e32 v17, 0x9000, v16
	v_mul_i32_i24_e32 v16, 0x9000, v16
	v_lshl_add_u64 v[16:17], s[96:97], 0, v[16:17]
	v_lshlrev_b32_e32 v32, 3, v93
	v_lshl_add_u64 v[18:19], v[16:17], 0, s[50:51]
	v_ashrrev_i32_e32 v33, 31, v32
	v_lshl_add_u64 v[24:25], v[16:17], 0, s[52:53]
	v_lshl_add_u64 v[16:17], v[18:19], 0, v[52:53]
	v_lshlrev_b64 v[68:69], 11, v[32:33]
	global_load_dwordx4 v[76:79], v[56:57], off offset:16
	global_load_dwordx4 v[72:75], v[56:57], off
	global_load_dwordx4 v[80:83], v[16:17], off offset:16
	global_load_dwordx4 v[94:97], v[16:17], off
	v_lshl_add_u64 v[20:21], v[24:25], 0, v[52:53]
	v_lshl_add_u64 v[16:17], v[18:19], 0, v[62:63]
	v_lshl_add_u64 v[32:33], s[22:23], 0, v[68:69]
	global_load_dwordx4 v[98:101], v[16:17], off offset:16
	global_load_dwordx4 v[102:105], v[16:17], off
	s_nop 0
	global_load_dwordx4 v[16:19], v[20:21], off offset:16
	s_nop 0
	global_load_dwordx4 v[20:23], v[20:21], off
	s_nop 0
	global_load_dwordx4 v[106:109], v[56:57], off offset:2064
	global_load_dwordx4 v[110:113], v[56:57], off offset:2048
	v_lshl_add_u64 v[28:29], v[24:25], 0, v[62:63]
	v_lshl_add_u64 v[32:33], v[32:33], 0, v[64:65]
	global_load_dwordx4 v[24:27], v[28:29], off offset:16
	s_nop 0
	global_load_dwordx4 v[28:31], v[28:29], off
	s_nop 0
	global_load_dwordx4 v[44:47], v[32:33], off
	global_load_dwordx4 v[40:43], v[32:33], off offset:1024
	v_ashrrev_i32_e32 v61, 31, v60
	v_lshlrev_b64 v[66:67], 11, v[60:61]
	v_lshl_add_u64 v[66:67], v[58:59], 0, v[66:67]
	v_lshl_add_u64 v[68:69], v[54:55], 0, v[68:69]
	s_mov_b64 s[6:7], 0xc500800
	v_lshl_add_u64 v[226:227], v[66:67], 0, s[6:7]
	global_load_dwordx4 v[32:35], v[226:227], off
	global_load_dwordx4 v[36:39], v[226:227], off offset:1024
	s_mov_b64 s[6:7], 0xc501000
	v_lshl_add_u64 v[224:225], v[66:67], 0, s[6:7]
	global_load_dwordx4 v[176:179], v[224:225], off
	global_load_dwordx4 v[180:183], v[224:225], off offset:1024
	s_mov_b64 s[6:7], 0xc501800
	v_lshl_add_u64 v[226:227], v[66:67], 0, s[6:7]
	global_load_dwordx4 v[184:187], v[226:227], off
	global_load_dwordx4 v[188:191], v[226:227], off offset:1024
	s_mov_b64 s[6:7], 0xc502000
	v_lshl_add_u64 v[224:225], v[66:67], 0, s[6:7]
	global_load_dwordx4 v[192:195], v[224:225], off
	global_load_dwordx4 v[196:199], v[224:225], off offset:1024
	s_mov_b64 s[6:7], 0xc502800
	v_lshl_add_u64 v[226:227], v[66:67], 0, s[6:7]
	global_load_dwordx4 v[200:203], v[226:227], off
	global_load_dwordx4 v[204:207], v[226:227], off offset:1024
	s_mov_b64 s[6:7], 0xc503000
	v_lshl_add_u64 v[224:225], v[66:67], 0, s[6:7]
	global_load_dwordx4 v[208:211], v[224:225], off
	global_load_dwordx4 v[212:215], v[224:225], off offset:1024
	s_mov_b64 s[6:7], 0xc503800
	v_lshl_add_u64 v[226:227], v[66:67], 0, s[6:7]
	global_load_dwordx4 v[216:219], v[226:227], off
	global_load_dwordx4 v[220:223], v[226:227], off offset:1024
	s_waitcnt vmcnt(16)
	v_pk_add_f32 v[100:101], v[100:101], 1.0 op_sel_hi:[1,0]
	v_pk_add_f32 v[70:71], v[96:97], 1.0 op_sel_hi:[1,0]
	v_pk_add_f32 v[84:85], v[94:95], 1.0 op_sel_hi:[1,0]
	v_pk_add_f32 v[82:83], v[82:83], 1.0 op_sel_hi:[1,0]
	v_pk_add_f32 v[80:81], v[80:81], 1.0 op_sel_hi:[1,0]
	v_pk_add_f32 v[94:95], v[104:105], 1.0 op_sel_hi:[1,0]
	v_pk_add_f32 v[96:97], v[102:103], 1.0 op_sel_hi:[1,0]
	v_pk_add_f32 v[98:99], v[98:99], 1.0 op_sel_hi:[1,0]
	v_pk_mul_f32 v[70:71], v[74:75], v[70:71]
	v_pk_mul_f32 v[72:73], v[72:73], v[84:85]
	v_pk_mul_f32 v[74:75], v[78:79], v[82:83]
	v_pk_mul_f32 v[76:77], v[76:77], v[80:81]
	v_pk_mul_f32 v[78:79], v[112:113], v[94:95]
	v_pk_mul_f32 v[80:81], v[110:111], v[96:97]
	v_pk_mul_f32 v[82:83], v[108:109], v[100:101]
	v_pk_mul_f32 v[84:85], v[106:107], v[98:99]
	s_waitcnt vmcnt(14)
	v_lshlrev_b32_e32 v96, 16, v42
	v_and_b32_e32 v61, 0xffff0000, v42
	v_lshlrev_b32_e32 v98, 16, v43
	v_and_b32_e32 v99, 0xffff0000, v43
	v_lshlrev_b32_e32 v43, 16, v45
	v_lshlrev_b32_e32 v42, 16, v44
	v_and_b32_e32 v45, 0xffff0000, v45
	v_and_b32_e32 v44, 0xffff0000, v44
	v_lshlrev_b32_e32 v103, 16, v47
	v_lshlrev_b32_e32 v102, 16, v46
	v_and_b32_e32 v47, 0xffff0000, v47
	v_and_b32_e32 v46, 0xffff0000, v46
	v_lshlrev_b32_e32 v94, 16, v40
	v_and_b32_e32 v95, 0xffff0000, v40
	v_pk_mul_f32 v[100:101], v[44:45], v[44:45]
	v_pk_mul_f32 v[104:105], v[46:47], v[46:47]
	v_lshlrev_b32_e32 v108, 16, v41
	v_pk_fma_f32 v[100:101], v[42:43], v[42:43], v[100:101]
	v_pk_fma_f32 v[104:105], v[102:103], v[102:103], v[104:105]
	v_mul_f32_e32 v97, v94, v94
	v_mul_f32_e32 v107, v95, v95
	v_and_b32_e32 v109, 0xffff0000, v41
	v_mul_f32_e32 v40, v108, v108
	v_mov_b32_e32 v106, v96
	v_pk_add_f32 v[100:101], v[100:101], v[100:101] op_sel_hi:[0,1]
	v_pk_add_f32 v[104:105], v[104:105], v[104:105] op_sel_hi:[0,1]
	v_pk_fma_f32 v[40:41], v[108:109], v[108:109], v[40:41] op_sel_hi:[1,1,0]
	v_pk_add_f32 v[106:107], v[96:97], v[106:107]
	v_mul_f32_e32 v40, v61, v61
	v_mul_f32_e32 v100, v98, v98
	v_mul_f32_e32 v104, v99, v99
	v_mul_f32_e32 v110, v96, v96
	v_mov_b32_e32 v111, v107
	v_pk_add_f32 v[40:41], v[110:111], v[40:41]
	v_pk_add_f32 v[100:101], v[100:101], v[104:105]
	v_pk_add_f32 v[40:41], v[40:41], v[100:101]
	v_add_f32_e32 v40, v40, v41
	s_nop 1
	v_add_f32_dpp v40, v40, v40 quad_perm:[1,0,3,2] row_mask:0xf bank_mask:0xf
	s_nop 1
	v_add_f32_dpp v40, v40, v40 quad_perm:[2,3,0,1] row_mask:0xf bank_mask:0xf
	s_nop 1
	v_add_f32_dpp v40, v40, v40 row_half_mirror row_mask:0xf bank_mask:0xf
	s_nop 1
	v_add_f32_dpp v40, v40, v40 row_ror:8 row_mask:0xf bank_mask:0xf
	v_mov_b32_e32 v41, v40
	s_nop 1
	v_permlane16_swap_b32_e32 v41, v40
	v_add_f32_e32 v40, v40, v41
	v_mov_b32_e32 v41, v40
	s_nop 1
	v_permlane32_swap_b32_e32 v41, v40
	v_add_f32_e32 v40, v40, v41
	v_fmamk_f32 v40, v40, 0x3a800000, v49
	v_mul_f32_e32 v41, 0x4f800000, v40
	v_cmp_gt_f32_e32 vcc, s8, v40
	s_nop 1
	v_cndmask_b32_e32 v40, v40, v41, vcc
	v_sqrt_f32_e32 v41, v40
	s_nop 0
	v_add_u32_e32 v97, -1, v41
	v_fma_f32 v100, -v97, v41, v40
	v_cmp_ge_f32_e64 s[0:1], 0, v100
	v_add_u32_e32 v100, 1, v41
	s_nop 0
	v_cndmask_b32_e64 v97, v41, v97, s[0:1]
	v_fma_f32 v41, -v100, v41, v40
	v_cmp_lt_f32_e64 s[0:1], 0, v41
	s_nop 1
	v_cndmask_b32_e64 v41, v97, v100, s[0:1]
	v_mul_f32_e32 v97, 0x37800000, v41
	v_cndmask_b32_e32 v41, v41, v97, vcc
	v_cmp_class_f32_e32 vcc, v40, v92
	s_nop 1
	v_cndmask_b32_e32 v40, v41, v40, vcc
	v_div_scale_f32 v41, s[0:1], v40, v40, 1.0
	v_rcp_f32_e32 v97, v41
	s_nop 0
	v_fma_f32 v100, -v41, v97, 1.0
	v_fmac_f32_e32 v97, v100, v97
	v_div_scale_f32 v100, vcc, 1.0, v40, 1.0
	v_mul_f32_e32 v101, v100, v97
	v_fma_f32 v104, -v41, v101, v100
	v_fmac_f32_e32 v101, v104, v97
	v_fma_f32 v41, -v41, v101, v100
	v_div_fmas_f32 v41, v41, v97, v101
	v_div_fixup_f32 v100, v41, v40, 1.0
	v_mov_b32_e32 v40, v42
	v_mov_b32_e32 v41, v44
	v_mov_b32_e32 v44, v43
	v_pk_mul_f32 v[40:41], v[100:101], v[40:41] op_sel_hi:[0,1]
	v_pk_mul_f32 v[42:43], v[100:101], v[44:45] op_sel_hi:[0,1]
	v_mov_b32_e32 v44, v102
	v_mov_b32_e32 v45, v46
	v_mov_b32_e32 v46, v103
	v_pk_fma_f32 v[42:43], v[70:71], v[42:43], v[22:23]
	v_pk_fma_f32 v[40:41], v[72:73], v[40:41], v[20:21]
	v_pk_mul_f32 v[44:45], v[100:101], v[44:45] op_sel_hi:[0,1]
	v_pk_mul_f32 v[46:47], v[100:101], v[46:47] op_sel_hi:[0,1]
	s_mov_b64 s[6:7], 0x0
	v_lshl_add_u64 v[104:105], s[6:7], 1, v[68:69]
	v_pk_fma_f32 v[46:47], v[74:75], v[46:47], v[18:19]
	v_pk_fma_f32 v[44:45], v[76:77], v[44:45], v[16:17]
	v_cvt_pk_bf16_f32 v40, v40, v41
	v_cvt_pk_bf16_f32 v41, v42, v43
	v_mov_b32_e32 v97, v61
	v_cvt_pk_bf16_f32 v42, v44, v45
	v_cvt_pk_bf16_f32 v43, v46, v47
	global_store_dwordx4 v[104:105], v[40:43], off
	v_pk_mul_f32 v[44:45], v[96:97], v[100:101] op_sel_hi:[1,0]
	v_pk_mul_f32 v[46:47], v[98:99], v[100:101] op_sel_hi:[1,0]
	v_pk_mul_f32 v[40:41], v[94:95], v[100:101] op_sel_hi:[1,0]
	v_pk_mul_f32 v[42:43], v[108:109], v[100:101] op_sel_hi:[1,0]
	v_pk_fma_f32 v[40:41], v[80:81], v[40:41], v[28:29]
	v_pk_fma_f32 v[42:43], v[78:79], v[42:43], v[30:31]
	v_pk_fma_f32 v[46:47], v[82:83], v[46:47], v[26:27]
	v_pk_fma_f32 v[44:45], v[84:85], v[44:45], v[24:25]
	v_cvt_pk_bf16_f32 v40, v40, v41
	v_cvt_pk_bf16_f32 v41, v42, v43
	s_nop 0
	v_cvt_pk_bf16_f32 v42, v44, v45
	v_cvt_pk_bf16_f32 v43, v46, v47
	global_store_dwordx4 v[104:105], v[40:43], off offset:1024
	s_nop 0
	s_nop 0
	s_nop 0
	s_nop 0
	s_nop 0
	s_nop 0
	s_nop 0
	s_nop 0
	s_waitcnt vmcnt(14)
	v_lshlrev_b32_e32 v96, 16, v38
	v_and_b32_e32 v61, 0xffff0000, v38
	v_lshlrev_b32_e32 v98, 16, v39
	v_and_b32_e32 v99, 0xffff0000, v39
	v_lshlrev_b32_e32 v39, 16, v33
	v_lshlrev_b32_e32 v38, 16, v32
	v_and_b32_e32 v33, 0xffff0000, v33
	v_and_b32_e32 v32, 0xffff0000, v32
	v_lshlrev_b32_e32 v103, 16, v35
	v_lshlrev_b32_e32 v102, 16, v34
	v_and_b32_e32 v35, 0xffff0000, v35
	v_and_b32_e32 v34, 0xffff0000, v34
	v_lshlrev_b32_e32 v94, 16, v36
	v_and_b32_e32 v95, 0xffff0000, v36
	v_pk_mul_f32 v[100:101], v[32:33], v[32:33]
	v_pk_mul_f32 v[104:105], v[34:35], v[34:35]
	v_lshlrev_b32_e32 v108, 16, v37
	v_pk_fma_f32 v[100:101], v[38:39], v[38:39], v[100:101]
	v_pk_fma_f32 v[104:105], v[102:103], v[102:103], v[104:105]
	v_mul_f32_e32 v97, v94, v94
	v_mul_f32_e32 v107, v95, v95
	v_and_b32_e32 v109, 0xffff0000, v37
	v_mul_f32_e32 v36, v108, v108
	v_mov_b32_e32 v106, v96
	v_pk_add_f32 v[100:101], v[100:101], v[100:101] op_sel_hi:[0,1]
	v_pk_add_f32 v[104:105], v[104:105], v[104:105] op_sel_hi:[0,1]
	v_pk_fma_f32 v[36:37], v[108:109], v[108:109], v[36:37] op_sel_hi:[1,1,0]
	v_pk_add_f32 v[106:107], v[96:97], v[106:107]
	v_mul_f32_e32 v36, v61, v61
	v_mul_f32_e32 v100, v98, v98
	v_mul_f32_e32 v104, v99, v99
	v_mul_f32_e32 v110, v96, v96
	v_mov_b32_e32 v111, v107
	v_pk_add_f32 v[36:37], v[110:111], v[36:37]
	v_pk_add_f32 v[100:101], v[100:101], v[104:105]
	v_pk_add_f32 v[36:37], v[36:37], v[100:101]
	v_add_f32_e32 v36, v36, v37
	s_nop 1
	v_add_f32_dpp v36, v36, v36 quad_perm:[1,0,3,2] row_mask:0xf bank_mask:0xf
	s_nop 1
	v_add_f32_dpp v36, v36, v36 quad_perm:[2,3,0,1] row_mask:0xf bank_mask:0xf
	s_nop 1
	v_add_f32_dpp v36, v36, v36 row_half_mirror row_mask:0xf bank_mask:0xf
	s_nop 1
	v_add_f32_dpp v36, v36, v36 row_ror:8 row_mask:0xf bank_mask:0xf
	v_mov_b32_e32 v37, v36
	s_nop 1
	v_permlane16_swap_b32_e32 v37, v36
	v_add_f32_e32 v36, v36, v37
	v_mov_b32_e32 v37, v36
	s_nop 1
	v_permlane32_swap_b32_e32 v37, v36
	v_add_f32_e32 v36, v36, v37
	v_fmamk_f32 v36, v36, 0x3a800000, v49
	v_mul_f32_e32 v37, 0x4f800000, v36
	v_cmp_gt_f32_e32 vcc, s8, v36
	s_nop 1
	v_cndmask_b32_e32 v36, v36, v37, vcc
	v_sqrt_f32_e32 v37, v36
	s_nop 0
	v_add_u32_e32 v97, -1, v37
	v_fma_f32 v100, -v97, v37, v36
	v_cmp_ge_f32_e64 s[0:1], 0, v100
	v_add_u32_e32 v100, 1, v37
	s_nop 0
	v_cndmask_b32_e64 v97, v37, v97, s[0:1]
	v_fma_f32 v37, -v100, v37, v36
	v_cmp_lt_f32_e64 s[0:1], 0, v37
	s_nop 1
	v_cndmask_b32_e64 v37, v97, v100, s[0:1]
	v_mul_f32_e32 v97, 0x37800000, v37
	v_cndmask_b32_e32 v37, v37, v97, vcc
	v_cmp_class_f32_e32 vcc, v36, v92
	s_nop 1
	v_cndmask_b32_e32 v36, v37, v36, vcc
	v_div_scale_f32 v37, s[0:1], v36, v36, 1.0
	v_rcp_f32_e32 v97, v37
	s_nop 0
	v_fma_f32 v100, -v37, v97, 1.0
	v_fmac_f32_e32 v97, v100, v97
	v_div_scale_f32 v100, vcc, 1.0, v36, 1.0
	v_mul_f32_e32 v101, v100, v97
	v_fma_f32 v104, -v37, v101, v100
	v_fmac_f32_e32 v101, v104, v97
	v_fma_f32 v37, -v37, v101, v100
	v_div_fmas_f32 v37, v37, v97, v101
	v_div_fixup_f32 v100, v37, v36, 1.0
	v_mov_b32_e32 v36, v38
	v_mov_b32_e32 v37, v32
	v_mov_b32_e32 v32, v39
	v_pk_mul_f32 v[36:37], v[100:101], v[36:37] op_sel_hi:[0,1]
	v_pk_mul_f32 v[38:39], v[100:101], v[32:33] op_sel_hi:[0,1]
	v_mov_b32_e32 v32, v102
	v_mov_b32_e32 v33, v34
	v_mov_b32_e32 v34, v103
	v_pk_fma_f32 v[38:39], v[70:71], v[38:39], v[22:23]
	v_pk_fma_f32 v[36:37], v[72:73], v[36:37], v[20:21]
	v_pk_mul_f32 v[32:33], v[100:101], v[32:33] op_sel_hi:[0,1]
	v_pk_mul_f32 v[34:35], v[100:101], v[34:35] op_sel_hi:[0,1]
	s_mov_b64 s[6:7], 0x400
	v_lshl_add_u64 v[104:105], s[6:7], 1, v[68:69]
	v_pk_fma_f32 v[34:35], v[74:75], v[34:35], v[18:19]
	v_pk_fma_f32 v[32:33], v[76:77], v[32:33], v[16:17]
	v_cvt_pk_bf16_f32 v36, v36, v37
	v_cvt_pk_bf16_f32 v37, v38, v39
	v_mov_b32_e32 v97, v61
	v_cvt_pk_bf16_f32 v38, v32, v33
	v_cvt_pk_bf16_f32 v39, v34, v35
	global_store_dwordx4 v[104:105], v[36:39], off
	v_pk_mul_f32 v[32:33], v[96:97], v[100:101] op_sel_hi:[1,0]
	v_pk_mul_f32 v[34:35], v[98:99], v[100:101] op_sel_hi:[1,0]
	v_pk_mul_f32 v[36:37], v[94:95], v[100:101] op_sel_hi:[1,0]
	v_pk_mul_f32 v[38:39], v[108:109], v[100:101] op_sel_hi:[1,0]
	v_pk_fma_f32 v[36:37], v[80:81], v[36:37], v[28:29]
	v_pk_fma_f32 v[38:39], v[78:79], v[38:39], v[30:31]
	v_pk_fma_f32 v[34:35], v[82:83], v[34:35], v[26:27]
	v_pk_fma_f32 v[32:33], v[84:85], v[32:33], v[24:25]
	v_cvt_pk_bf16_f32 v36, v36, v37
	v_cvt_pk_bf16_f32 v37, v38, v39
	s_nop 0
	v_cvt_pk_bf16_f32 v38, v32, v33
	v_cvt_pk_bf16_f32 v39, v34, v35
	global_store_dwordx4 v[104:105], v[36:39], off offset:1024
	s_nop 0
	s_nop 0
	s_nop 0
	s_nop 0
	s_nop 0
	s_nop 0
	s_nop 0
	s_nop 0
	s_waitcnt vmcnt(14)
	v_lshlrev_b32_e32 v96, 16, v182
	v_and_b32_e32 v61, 0xffff0000, v182
	v_lshlrev_b32_e32 v98, 16, v183
	v_and_b32_e32 v99, 0xffff0000, v183
	v_lshlrev_b32_e32 v183, 16, v177
	v_lshlrev_b32_e32 v182, 16, v176
	v_and_b32_e32 v177, 0xffff0000, v177
	v_and_b32_e32 v176, 0xffff0000, v176
	v_lshlrev_b32_e32 v103, 16, v179
	v_lshlrev_b32_e32 v102, 16, v178
	v_and_b32_e32 v179, 0xffff0000, v179
	v_and_b32_e32 v178, 0xffff0000, v178
	v_lshlrev_b32_e32 v94, 16, v180
	v_and_b32_e32 v95, 0xffff0000, v180
	v_pk_mul_f32 v[100:101], v[176:177], v[176:177]
	v_pk_mul_f32 v[104:105], v[178:179], v[178:179]
	v_lshlrev_b32_e32 v108, 16, v181
	v_pk_fma_f32 v[100:101], v[182:183], v[182:183], v[100:101]
	v_pk_fma_f32 v[104:105], v[102:103], v[102:103], v[104:105]
	v_mul_f32_e32 v97, v94, v94
	v_mul_f32_e32 v107, v95, v95
	v_and_b32_e32 v109, 0xffff0000, v181
	v_mul_f32_e32 v180, v108, v108
	v_mov_b32_e32 v106, v96
	v_pk_add_f32 v[100:101], v[100:101], v[100:101] op_sel_hi:[0,1]
	v_pk_add_f32 v[104:105], v[104:105], v[104:105] op_sel_hi:[0,1]
	v_pk_fma_f32 v[180:181], v[108:109], v[108:109], v[180:181] op_sel_hi:[1,1,0]
	v_pk_add_f32 v[106:107], v[96:97], v[106:107]
	v_mul_f32_e32 v180, v61, v61
	v_mul_f32_e32 v100, v98, v98
	v_mul_f32_e32 v104, v99, v99
	v_mul_f32_e32 v110, v96, v96
	v_mov_b32_e32 v111, v107
	v_pk_add_f32 v[180:181], v[110:111], v[180:181]
	v_pk_add_f32 v[100:101], v[100:101], v[104:105]
	v_pk_add_f32 v[180:181], v[180:181], v[100:101]
	v_add_f32_e32 v180, v180, v181
	s_nop 1
	v_add_f32_dpp v180, v180, v180 quad_perm:[1,0,3,2] row_mask:0xf bank_mask:0xf
	s_nop 1
	v_add_f32_dpp v180, v180, v180 quad_perm:[2,3,0,1] row_mask:0xf bank_mask:0xf
	s_nop 1
	v_add_f32_dpp v180, v180, v180 row_half_mirror row_mask:0xf bank_mask:0xf
	s_nop 1
	v_add_f32_dpp v180, v180, v180 row_ror:8 row_mask:0xf bank_mask:0xf
	v_mov_b32_e32 v181, v180
	s_nop 1
	v_permlane16_swap_b32_e32 v181, v180
	v_add_f32_e32 v180, v180, v181
	v_mov_b32_e32 v181, v180
	s_nop 1
	v_permlane32_swap_b32_e32 v181, v180
	v_add_f32_e32 v180, v180, v181
	v_fmamk_f32 v180, v180, 0x3a800000, v49
	v_mul_f32_e32 v181, 0x4f800000, v180
	v_cmp_gt_f32_e32 vcc, s8, v180
	s_nop 1
	v_cndmask_b32_e32 v180, v180, v181, vcc
	v_sqrt_f32_e32 v181, v180
	s_nop 0
	v_add_u32_e32 v97, -1, v181
	v_fma_f32 v100, -v97, v181, v180
	v_cmp_ge_f32_e64 s[0:1], 0, v100
	v_add_u32_e32 v100, 1, v181
	s_nop 0
	v_cndmask_b32_e64 v97, v181, v97, s[0:1]
	v_fma_f32 v181, -v100, v181, v180
	v_cmp_lt_f32_e64 s[0:1], 0, v181
	s_nop 1
	v_cndmask_b32_e64 v181, v97, v100, s[0:1]
	v_mul_f32_e32 v97, 0x37800000, v181
	v_cndmask_b32_e32 v181, v181, v97, vcc
	v_cmp_class_f32_e32 vcc, v180, v92
	s_nop 1
	v_cndmask_b32_e32 v180, v181, v180, vcc
	v_div_scale_f32 v181, s[0:1], v180, v180, 1.0
	v_rcp_f32_e32 v97, v181
	s_nop 0
	v_fma_f32 v100, -v181, v97, 1.0
	v_fmac_f32_e32 v97, v100, v97
	v_div_scale_f32 v100, vcc, 1.0, v180, 1.0
	v_mul_f32_e32 v101, v100, v97
	v_fma_f32 v104, -v181, v101, v100
	v_fmac_f32_e32 v101, v104, v97
	v_fma_f32 v181, -v181, v101, v100
	v_div_fmas_f32 v181, v181, v97, v101
	v_div_fixup_f32 v100, v181, v180, 1.0
	v_mov_b32_e32 v180, v182
	v_mov_b32_e32 v181, v176
	v_mov_b32_e32 v176, v183
	v_pk_mul_f32 v[180:181], v[100:101], v[180:181] op_sel_hi:[0,1]
	v_pk_mul_f32 v[182:183], v[100:101], v[176:177] op_sel_hi:[0,1]
	v_mov_b32_e32 v176, v102
	v_mov_b32_e32 v177, v178
	v_mov_b32_e32 v178, v103
	v_pk_fma_f32 v[182:183], v[70:71], v[182:183], v[22:23]
	v_pk_fma_f32 v[180:181], v[72:73], v[180:181], v[20:21]
	v_pk_mul_f32 v[176:177], v[100:101], v[176:177] op_sel_hi:[0,1]
	v_pk_mul_f32 v[178:179], v[100:101], v[178:179] op_sel_hi:[0,1]
	s_mov_b64 s[6:7], 0x800
	v_lshl_add_u64 v[104:105], s[6:7], 1, v[68:69]
	v_pk_fma_f32 v[178:179], v[74:75], v[178:179], v[18:19]
	v_pk_fma_f32 v[176:177], v[76:77], v[176:177], v[16:17]
	v_cvt_pk_bf16_f32 v180, v180, v181
	v_cvt_pk_bf16_f32 v181, v182, v183
	v_mov_b32_e32 v97, v61
	v_cvt_pk_bf16_f32 v182, v176, v177
	v_cvt_pk_bf16_f32 v183, v178, v179
	global_store_dwordx4 v[104:105], v[180:183], off
	v_pk_mul_f32 v[176:177], v[96:97], v[100:101] op_sel_hi:[1,0]
	v_pk_mul_f32 v[178:179], v[98:99], v[100:101] op_sel_hi:[1,0]
	v_pk_mul_f32 v[180:181], v[94:95], v[100:101] op_sel_hi:[1,0]
	v_pk_mul_f32 v[182:183], v[108:109], v[100:101] op_sel_hi:[1,0]
	v_pk_fma_f32 v[180:181], v[80:81], v[180:181], v[28:29]
	v_pk_fma_f32 v[182:183], v[78:79], v[182:183], v[30:31]
	v_pk_fma_f32 v[178:179], v[82:83], v[178:179], v[26:27]
	v_pk_fma_f32 v[176:177], v[84:85], v[176:177], v[24:25]
	v_cvt_pk_bf16_f32 v180, v180, v181
	v_cvt_pk_bf16_f32 v181, v182, v183
	s_nop 0
	v_cvt_pk_bf16_f32 v182, v176, v177
	v_cvt_pk_bf16_f32 v183, v178, v179
	global_store_dwordx4 v[104:105], v[180:183], off offset:1024
	s_nop 0
	s_nop 0
	s_nop 0
	s_nop 0
	s_nop 0
	s_nop 0
	s_nop 0
	s_nop 0
	s_waitcnt vmcnt(14)
	v_lshlrev_b32_e32 v96, 16, v190
	v_and_b32_e32 v61, 0xffff0000, v190
	v_lshlrev_b32_e32 v98, 16, v191
	v_and_b32_e32 v99, 0xffff0000, v191
	v_lshlrev_b32_e32 v191, 16, v185
	v_lshlrev_b32_e32 v190, 16, v184
	v_and_b32_e32 v185, 0xffff0000, v185
	v_and_b32_e32 v184, 0xffff0000, v184
	v_lshlrev_b32_e32 v103, 16, v187
	v_lshlrev_b32_e32 v102, 16, v186
	v_and_b32_e32 v187, 0xffff0000, v187
	v_and_b32_e32 v186, 0xffff0000, v186
	v_lshlrev_b32_e32 v94, 16, v188
	v_and_b32_e32 v95, 0xffff0000, v188
	v_pk_mul_f32 v[100:101], v[184:185], v[184:185]
	v_pk_mul_f32 v[104:105], v[186:187], v[186:187]
	v_lshlrev_b32_e32 v108, 16, v189
	v_pk_fma_f32 v[100:101], v[190:191], v[190:191], v[100:101]
	v_pk_fma_f32 v[104:105], v[102:103], v[102:103], v[104:105]
	v_mul_f32_e32 v97, v94, v94
	v_mul_f32_e32 v107, v95, v95
	v_and_b32_e32 v109, 0xffff0000, v189
	v_mul_f32_e32 v188, v108, v108
	v_mov_b32_e32 v106, v96
	v_pk_add_f32 v[100:101], v[100:101], v[100:101] op_sel_hi:[0,1]
	v_pk_add_f32 v[104:105], v[104:105], v[104:105] op_sel_hi:[0,1]
	v_pk_fma_f32 v[188:189], v[108:109], v[108:109], v[188:189] op_sel_hi:[1,1,0]
	v_pk_add_f32 v[106:107], v[96:97], v[106:107]
	v_mul_f32_e32 v188, v61, v61
	v_mul_f32_e32 v100, v98, v98
	v_mul_f32_e32 v104, v99, v99
	v_mul_f32_e32 v110, v96, v96
	v_mov_b32_e32 v111, v107
	v_pk_add_f32 v[188:189], v[110:111], v[188:189]
	v_pk_add_f32 v[100:101], v[100:101], v[104:105]
	v_pk_add_f32 v[188:189], v[188:189], v[100:101]
	v_add_f32_e32 v188, v188, v189
	s_nop 1
	v_add_f32_dpp v188, v188, v188 quad_perm:[1,0,3,2] row_mask:0xf bank_mask:0xf
	s_nop 1
	v_add_f32_dpp v188, v188, v188 quad_perm:[2,3,0,1] row_mask:0xf bank_mask:0xf
	s_nop 1
	v_add_f32_dpp v188, v188, v188 row_half_mirror row_mask:0xf bank_mask:0xf
	s_nop 1
	v_add_f32_dpp v188, v188, v188 row_ror:8 row_mask:0xf bank_mask:0xf
	v_mov_b32_e32 v189, v188
	s_nop 1
	v_permlane16_swap_b32_e32 v189, v188
	v_add_f32_e32 v188, v188, v189
	v_mov_b32_e32 v189, v188
	s_nop 1
	v_permlane32_swap_b32_e32 v189, v188
	v_add_f32_e32 v188, v188, v189
	v_fmamk_f32 v188, v188, 0x3a800000, v49
	v_mul_f32_e32 v189, 0x4f800000, v188
	v_cmp_gt_f32_e32 vcc, s8, v188
	s_nop 1
	v_cndmask_b32_e32 v188, v188, v189, vcc
	v_sqrt_f32_e32 v189, v188
	s_nop 0
	v_add_u32_e32 v97, -1, v189
	v_fma_f32 v100, -v97, v189, v188
	v_cmp_ge_f32_e64 s[0:1], 0, v100
	v_add_u32_e32 v100, 1, v189
	s_nop 0
	v_cndmask_b32_e64 v97, v189, v97, s[0:1]
	v_fma_f32 v189, -v100, v189, v188
	v_cmp_lt_f32_e64 s[0:1], 0, v189
	s_nop 1
	v_cndmask_b32_e64 v189, v97, v100, s[0:1]
	v_mul_f32_e32 v97, 0x37800000, v189
	v_cndmask_b32_e32 v189, v189, v97, vcc
	v_cmp_class_f32_e32 vcc, v188, v92
	s_nop 1
	v_cndmask_b32_e32 v188, v189, v188, vcc
	v_div_scale_f32 v189, s[0:1], v188, v188, 1.0
	v_rcp_f32_e32 v97, v189
	s_nop 0
	v_fma_f32 v100, -v189, v97, 1.0
	v_fmac_f32_e32 v97, v100, v97
	v_div_scale_f32 v100, vcc, 1.0, v188, 1.0
	v_mul_f32_e32 v101, v100, v97
	v_fma_f32 v104, -v189, v101, v100
	v_fmac_f32_e32 v101, v104, v97
	v_fma_f32 v189, -v189, v101, v100
	v_div_fmas_f32 v189, v189, v97, v101
	v_div_fixup_f32 v100, v189, v188, 1.0
	v_mov_b32_e32 v188, v190
	v_mov_b32_e32 v189, v184
	v_mov_b32_e32 v184, v191
	v_pk_mul_f32 v[188:189], v[100:101], v[188:189] op_sel_hi:[0,1]
	v_pk_mul_f32 v[190:191], v[100:101], v[184:185] op_sel_hi:[0,1]
	v_mov_b32_e32 v184, v102
	v_mov_b32_e32 v185, v186
	v_mov_b32_e32 v186, v103
	v_pk_fma_f32 v[190:191], v[70:71], v[190:191], v[22:23]
	v_pk_fma_f32 v[188:189], v[72:73], v[188:189], v[20:21]
	v_pk_mul_f32 v[184:185], v[100:101], v[184:185] op_sel_hi:[0,1]
	v_pk_mul_f32 v[186:187], v[100:101], v[186:187] op_sel_hi:[0,1]
	s_mov_b64 s[6:7], 0xc00
	v_lshl_add_u64 v[104:105], s[6:7], 1, v[68:69]
	v_pk_fma_f32 v[186:187], v[74:75], v[186:187], v[18:19]
	v_pk_fma_f32 v[184:185], v[76:77], v[184:185], v[16:17]
	v_cvt_pk_bf16_f32 v188, v188, v189
	v_cvt_pk_bf16_f32 v189, v190, v191
	v_mov_b32_e32 v97, v61
	v_cvt_pk_bf16_f32 v190, v184, v185
	v_cvt_pk_bf16_f32 v191, v186, v187
	global_store_dwordx4 v[104:105], v[188:191], off
	v_pk_mul_f32 v[184:185], v[96:97], v[100:101] op_sel_hi:[1,0]
	v_pk_mul_f32 v[186:187], v[98:99], v[100:101] op_sel_hi:[1,0]
	v_pk_mul_f32 v[188:189], v[94:95], v[100:101] op_sel_hi:[1,0]
	v_pk_mul_f32 v[190:191], v[108:109], v[100:101] op_sel_hi:[1,0]
	v_pk_fma_f32 v[188:189], v[80:81], v[188:189], v[28:29]
	v_pk_fma_f32 v[190:191], v[78:79], v[190:191], v[30:31]
	v_pk_fma_f32 v[186:187], v[82:83], v[186:187], v[26:27]
	v_pk_fma_f32 v[184:185], v[84:85], v[184:185], v[24:25]
	v_cvt_pk_bf16_f32 v188, v188, v189
	v_cvt_pk_bf16_f32 v189, v190, v191
	s_nop 0
	v_cvt_pk_bf16_f32 v190, v184, v185
	v_cvt_pk_bf16_f32 v191, v186, v187
	global_store_dwordx4 v[104:105], v[188:191], off offset:1024
	s_nop 0
	s_nop 0
	s_nop 0
	s_nop 0
	s_nop 0
	s_nop 0
	s_nop 0
	s_nop 0
	s_waitcnt vmcnt(14)
	v_lshlrev_b32_e32 v96, 16, v198
	v_and_b32_e32 v61, 0xffff0000, v198
	v_lshlrev_b32_e32 v98, 16, v199
	v_and_b32_e32 v99, 0xffff0000, v199
	v_lshlrev_b32_e32 v199, 16, v193
	v_lshlrev_b32_e32 v198, 16, v192
	v_and_b32_e32 v193, 0xffff0000, v193
	v_and_b32_e32 v192, 0xffff0000, v192
	v_lshlrev_b32_e32 v103, 16, v195
	v_lshlrev_b32_e32 v102, 16, v194
	v_and_b32_e32 v195, 0xffff0000, v195
	v_and_b32_e32 v194, 0xffff0000, v194
	v_lshlrev_b32_e32 v94, 16, v196
	v_and_b32_e32 v95, 0xffff0000, v196
	v_pk_mul_f32 v[100:101], v[192:193], v[192:193]
	v_pk_mul_f32 v[104:105], v[194:195], v[194:195]
	v_lshlrev_b32_e32 v108, 16, v197
	v_pk_fma_f32 v[100:101], v[198:199], v[198:199], v[100:101]
	v_pk_fma_f32 v[104:105], v[102:103], v[102:103], v[104:105]
	v_mul_f32_e32 v97, v94, v94
	v_mul_f32_e32 v107, v95, v95
	v_and_b32_e32 v109, 0xffff0000, v197
	v_mul_f32_e32 v196, v108, v108
	v_mov_b32_e32 v106, v96
	v_pk_add_f32 v[100:101], v[100:101], v[100:101] op_sel_hi:[0,1]
	v_pk_add_f32 v[104:105], v[104:105], v[104:105] op_sel_hi:[0,1]
	v_pk_fma_f32 v[196:197], v[108:109], v[108:109], v[196:197] op_sel_hi:[1,1,0]
	v_pk_add_f32 v[106:107], v[96:97], v[106:107]
	v_mul_f32_e32 v196, v61, v61
	v_mul_f32_e32 v100, v98, v98
	v_mul_f32_e32 v104, v99, v99
	v_mul_f32_e32 v110, v96, v96
	v_mov_b32_e32 v111, v107
	v_pk_add_f32 v[196:197], v[110:111], v[196:197]
	v_pk_add_f32 v[100:101], v[100:101], v[104:105]
	v_pk_add_f32 v[196:197], v[196:197], v[100:101]
	v_add_f32_e32 v196, v196, v197
	s_nop 1
	v_add_f32_dpp v196, v196, v196 quad_perm:[1,0,3,2] row_mask:0xf bank_mask:0xf
	s_nop 1
	v_add_f32_dpp v196, v196, v196 quad_perm:[2,3,0,1] row_mask:0xf bank_mask:0xf
	s_nop 1
	v_add_f32_dpp v196, v196, v196 row_half_mirror row_mask:0xf bank_mask:0xf
	s_nop 1
	v_add_f32_dpp v196, v196, v196 row_ror:8 row_mask:0xf bank_mask:0xf
	v_mov_b32_e32 v197, v196
	s_nop 1
	v_permlane16_swap_b32_e32 v197, v196
	v_add_f32_e32 v196, v196, v197
	v_mov_b32_e32 v197, v196
	s_nop 1
	v_permlane32_swap_b32_e32 v197, v196
	v_add_f32_e32 v196, v196, v197
	v_fmamk_f32 v196, v196, 0x3a800000, v49
	v_mul_f32_e32 v197, 0x4f800000, v196
	v_cmp_gt_f32_e32 vcc, s8, v196
	s_nop 1
	v_cndmask_b32_e32 v196, v196, v197, vcc
	v_sqrt_f32_e32 v197, v196
	s_nop 0
	v_add_u32_e32 v97, -1, v197
	v_fma_f32 v100, -v97, v197, v196
	v_cmp_ge_f32_e64 s[0:1], 0, v100
	v_add_u32_e32 v100, 1, v197
	s_nop 0
	v_cndmask_b32_e64 v97, v197, v97, s[0:1]
	v_fma_f32 v197, -v100, v197, v196
	v_cmp_lt_f32_e64 s[0:1], 0, v197
	s_nop 1
	v_cndmask_b32_e64 v197, v97, v100, s[0:1]
	v_mul_f32_e32 v97, 0x37800000, v197
	v_cndmask_b32_e32 v197, v197, v97, vcc
	v_cmp_class_f32_e32 vcc, v196, v92
	s_nop 1
	v_cndmask_b32_e32 v196, v197, v196, vcc
	v_div_scale_f32 v197, s[0:1], v196, v196, 1.0
	v_rcp_f32_e32 v97, v197
	s_nop 0
	v_fma_f32 v100, -v197, v97, 1.0
	v_fmac_f32_e32 v97, v100, v97
	v_div_scale_f32 v100, vcc, 1.0, v196, 1.0
	v_mul_f32_e32 v101, v100, v97
	v_fma_f32 v104, -v197, v101, v100
	v_fmac_f32_e32 v101, v104, v97
	v_fma_f32 v197, -v197, v101, v100
	v_div_fmas_f32 v197, v197, v97, v101
	v_div_fixup_f32 v100, v197, v196, 1.0
	v_mov_b32_e32 v196, v198
	v_mov_b32_e32 v197, v192
	v_mov_b32_e32 v192, v199
	v_pk_mul_f32 v[196:197], v[100:101], v[196:197] op_sel_hi:[0,1]
	v_pk_mul_f32 v[198:199], v[100:101], v[192:193] op_sel_hi:[0,1]
	v_mov_b32_e32 v192, v102
	v_mov_b32_e32 v193, v194
	v_mov_b32_e32 v194, v103
	v_pk_fma_f32 v[198:199], v[70:71], v[198:199], v[22:23]
	v_pk_fma_f32 v[196:197], v[72:73], v[196:197], v[20:21]
	v_pk_mul_f32 v[192:193], v[100:101], v[192:193] op_sel_hi:[0,1]
	v_pk_mul_f32 v[194:195], v[100:101], v[194:195] op_sel_hi:[0,1]
	s_mov_b64 s[6:7], 0x1000
	v_lshl_add_u64 v[104:105], s[6:7], 1, v[68:69]
	v_pk_fma_f32 v[194:195], v[74:75], v[194:195], v[18:19]
	v_pk_fma_f32 v[192:193], v[76:77], v[192:193], v[16:17]
	v_cvt_pk_bf16_f32 v196, v196, v197
	v_cvt_pk_bf16_f32 v197, v198, v199
	v_mov_b32_e32 v97, v61
	v_cvt_pk_bf16_f32 v198, v192, v193
	v_cvt_pk_bf16_f32 v199, v194, v195
	global_store_dwordx4 v[104:105], v[196:199], off
	v_pk_mul_f32 v[192:193], v[96:97], v[100:101] op_sel_hi:[1,0]
	v_pk_mul_f32 v[194:195], v[98:99], v[100:101] op_sel_hi:[1,0]
	v_pk_mul_f32 v[196:197], v[94:95], v[100:101] op_sel_hi:[1,0]
	v_pk_mul_f32 v[198:199], v[108:109], v[100:101] op_sel_hi:[1,0]
	v_pk_fma_f32 v[196:197], v[80:81], v[196:197], v[28:29]
	v_pk_fma_f32 v[198:199], v[78:79], v[198:199], v[30:31]
	v_pk_fma_f32 v[194:195], v[82:83], v[194:195], v[26:27]
	v_pk_fma_f32 v[192:193], v[84:85], v[192:193], v[24:25]
	v_cvt_pk_bf16_f32 v196, v196, v197
	v_cvt_pk_bf16_f32 v197, v198, v199
	s_nop 0
	v_cvt_pk_bf16_f32 v198, v192, v193
	v_cvt_pk_bf16_f32 v199, v194, v195
	global_store_dwordx4 v[104:105], v[196:199], off offset:1024
	s_nop 0
	s_nop 0
	s_nop 0
	s_nop 0
	s_nop 0
	s_nop 0
	s_nop 0
	s_nop 0
	s_waitcnt vmcnt(14)
	v_lshlrev_b32_e32 v96, 16, v206
	v_and_b32_e32 v61, 0xffff0000, v206
	v_lshlrev_b32_e32 v98, 16, v207
	v_and_b32_e32 v99, 0xffff0000, v207
	v_lshlrev_b32_e32 v207, 16, v201
	v_lshlrev_b32_e32 v206, 16, v200
	v_and_b32_e32 v201, 0xffff0000, v201
	v_and_b32_e32 v200, 0xffff0000, v200
	v_lshlrev_b32_e32 v103, 16, v203
	v_lshlrev_b32_e32 v102, 16, v202
	v_and_b32_e32 v203, 0xffff0000, v203
	v_and_b32_e32 v202, 0xffff0000, v202
	v_lshlrev_b32_e32 v94, 16, v204
	v_and_b32_e32 v95, 0xffff0000, v204
	v_pk_mul_f32 v[100:101], v[200:201], v[200:201]
	v_pk_mul_f32 v[104:105], v[202:203], v[202:203]
	v_lshlrev_b32_e32 v108, 16, v205
	v_pk_fma_f32 v[100:101], v[206:207], v[206:207], v[100:101]
	v_pk_fma_f32 v[104:105], v[102:103], v[102:103], v[104:105]
	v_mul_f32_e32 v97, v94, v94
	v_mul_f32_e32 v107, v95, v95
	v_and_b32_e32 v109, 0xffff0000, v205
	v_mul_f32_e32 v204, v108, v108
	v_mov_b32_e32 v106, v96
	v_pk_add_f32 v[100:101], v[100:101], v[100:101] op_sel_hi:[0,1]
	v_pk_add_f32 v[104:105], v[104:105], v[104:105] op_sel_hi:[0,1]
	v_pk_fma_f32 v[204:205], v[108:109], v[108:109], v[204:205] op_sel_hi:[1,1,0]
	v_pk_add_f32 v[106:107], v[96:97], v[106:107]
	v_mul_f32_e32 v204, v61, v61
	v_mul_f32_e32 v100, v98, v98
	v_mul_f32_e32 v104, v99, v99
	v_mul_f32_e32 v110, v96, v96
	v_mov_b32_e32 v111, v107
	v_pk_add_f32 v[204:205], v[110:111], v[204:205]
	v_pk_add_f32 v[100:101], v[100:101], v[104:105]
	v_pk_add_f32 v[204:205], v[204:205], v[100:101]
	v_add_f32_e32 v204, v204, v205
	s_nop 1
	v_add_f32_dpp v204, v204, v204 quad_perm:[1,0,3,2] row_mask:0xf bank_mask:0xf
	s_nop 1
	v_add_f32_dpp v204, v204, v204 quad_perm:[2,3,0,1] row_mask:0xf bank_mask:0xf
	s_nop 1
	v_add_f32_dpp v204, v204, v204 row_half_mirror row_mask:0xf bank_mask:0xf
	s_nop 1
	v_add_f32_dpp v204, v204, v204 row_ror:8 row_mask:0xf bank_mask:0xf
	v_mov_b32_e32 v205, v204
	s_nop 1
	v_permlane16_swap_b32_e32 v205, v204
	v_add_f32_e32 v204, v204, v205
	v_mov_b32_e32 v205, v204
	s_nop 1
	v_permlane32_swap_b32_e32 v205, v204
	v_add_f32_e32 v204, v204, v205
	v_fmamk_f32 v204, v204, 0x3a800000, v49
	v_mul_f32_e32 v205, 0x4f800000, v204
	v_cmp_gt_f32_e32 vcc, s8, v204
	s_nop 1
	v_cndmask_b32_e32 v204, v204, v205, vcc
	v_sqrt_f32_e32 v205, v204
	s_nop 0
	v_add_u32_e32 v97, -1, v205
	v_fma_f32 v100, -v97, v205, v204
	v_cmp_ge_f32_e64 s[0:1], 0, v100
	v_add_u32_e32 v100, 1, v205
	s_nop 0
	v_cndmask_b32_e64 v97, v205, v97, s[0:1]
	v_fma_f32 v205, -v100, v205, v204
	v_cmp_lt_f32_e64 s[0:1], 0, v205
	s_nop 1
	v_cndmask_b32_e64 v205, v97, v100, s[0:1]
	v_mul_f32_e32 v97, 0x37800000, v205
	v_cndmask_b32_e32 v205, v205, v97, vcc
	v_cmp_class_f32_e32 vcc, v204, v92
	s_nop 1
	v_cndmask_b32_e32 v204, v205, v204, vcc
	v_div_scale_f32 v205, s[0:1], v204, v204, 1.0
	v_rcp_f32_e32 v97, v205
	s_nop 0
	v_fma_f32 v100, -v205, v97, 1.0
	v_fmac_f32_e32 v97, v100, v97
	v_div_scale_f32 v100, vcc, 1.0, v204, 1.0
	v_mul_f32_e32 v101, v100, v97
	v_fma_f32 v104, -v205, v101, v100
	v_fmac_f32_e32 v101, v104, v97
	v_fma_f32 v205, -v205, v101, v100
	v_div_fmas_f32 v205, v205, v97, v101
	v_div_fixup_f32 v100, v205, v204, 1.0
	v_mov_b32_e32 v204, v206
	v_mov_b32_e32 v205, v200
	v_mov_b32_e32 v200, v207
	v_pk_mul_f32 v[204:205], v[100:101], v[204:205] op_sel_hi:[0,1]
	v_pk_mul_f32 v[206:207], v[100:101], v[200:201] op_sel_hi:[0,1]
	v_mov_b32_e32 v200, v102
	v_mov_b32_e32 v201, v202
	v_mov_b32_e32 v202, v103
	v_pk_fma_f32 v[206:207], v[70:71], v[206:207], v[22:23]
	v_pk_fma_f32 v[204:205], v[72:73], v[204:205], v[20:21]
	v_pk_mul_f32 v[200:201], v[100:101], v[200:201] op_sel_hi:[0,1]
	v_pk_mul_f32 v[202:203], v[100:101], v[202:203] op_sel_hi:[0,1]
	s_mov_b64 s[6:7], 0x1400
	v_lshl_add_u64 v[104:105], s[6:7], 1, v[68:69]
	v_pk_fma_f32 v[202:203], v[74:75], v[202:203], v[18:19]
	v_pk_fma_f32 v[200:201], v[76:77], v[200:201], v[16:17]
	v_cvt_pk_bf16_f32 v204, v204, v205
	v_cvt_pk_bf16_f32 v205, v206, v207
	v_mov_b32_e32 v97, v61
	v_cvt_pk_bf16_f32 v206, v200, v201
	v_cvt_pk_bf16_f32 v207, v202, v203
	global_store_dwordx4 v[104:105], v[204:207], off
	v_pk_mul_f32 v[200:201], v[96:97], v[100:101] op_sel_hi:[1,0]
	v_pk_mul_f32 v[202:203], v[98:99], v[100:101] op_sel_hi:[1,0]
	v_pk_mul_f32 v[204:205], v[94:95], v[100:101] op_sel_hi:[1,0]
	v_pk_mul_f32 v[206:207], v[108:109], v[100:101] op_sel_hi:[1,0]
	v_pk_fma_f32 v[204:205], v[80:81], v[204:205], v[28:29]
	v_pk_fma_f32 v[206:207], v[78:79], v[206:207], v[30:31]
	v_pk_fma_f32 v[202:203], v[82:83], v[202:203], v[26:27]
	v_pk_fma_f32 v[200:201], v[84:85], v[200:201], v[24:25]
	v_cvt_pk_bf16_f32 v204, v204, v205
	v_cvt_pk_bf16_f32 v205, v206, v207
	s_nop 0
	v_cvt_pk_bf16_f32 v206, v200, v201
	v_cvt_pk_bf16_f32 v207, v202, v203
	global_store_dwordx4 v[104:105], v[204:207], off offset:1024
	s_nop 0
	s_nop 0
	s_nop 0
	s_nop 0
	s_nop 0
	s_nop 0
	s_nop 0
	s_nop 0
	s_waitcnt vmcnt(14)
	v_lshlrev_b32_e32 v96, 16, v214
	v_and_b32_e32 v61, 0xffff0000, v214
	v_lshlrev_b32_e32 v98, 16, v215
	v_and_b32_e32 v99, 0xffff0000, v215
	v_lshlrev_b32_e32 v215, 16, v209
	v_lshlrev_b32_e32 v214, 16, v208
	v_and_b32_e32 v209, 0xffff0000, v209
	v_and_b32_e32 v208, 0xffff0000, v208
	v_lshlrev_b32_e32 v103, 16, v211
	v_lshlrev_b32_e32 v102, 16, v210
	v_and_b32_e32 v211, 0xffff0000, v211
	v_and_b32_e32 v210, 0xffff0000, v210
	v_lshlrev_b32_e32 v94, 16, v212
	v_and_b32_e32 v95, 0xffff0000, v212
	v_pk_mul_f32 v[100:101], v[208:209], v[208:209]
	v_pk_mul_f32 v[104:105], v[210:211], v[210:211]
	v_lshlrev_b32_e32 v108, 16, v213
	v_pk_fma_f32 v[100:101], v[214:215], v[214:215], v[100:101]
	v_pk_fma_f32 v[104:105], v[102:103], v[102:103], v[104:105]
	v_mul_f32_e32 v97, v94, v94
	v_mul_f32_e32 v107, v95, v95
	v_and_b32_e32 v109, 0xffff0000, v213
	v_mul_f32_e32 v212, v108, v108
	v_mov_b32_e32 v106, v96
	v_pk_add_f32 v[100:101], v[100:101], v[100:101] op_sel_hi:[0,1]
	v_pk_add_f32 v[104:105], v[104:105], v[104:105] op_sel_hi:[0,1]
	v_pk_fma_f32 v[212:213], v[108:109], v[108:109], v[212:213] op_sel_hi:[1,1,0]
	v_pk_add_f32 v[106:107], v[96:97], v[106:107]
	v_mul_f32_e32 v212, v61, v61
	v_mul_f32_e32 v100, v98, v98
	v_mul_f32_e32 v104, v99, v99
	v_mul_f32_e32 v110, v96, v96
	v_mov_b32_e32 v111, v107
	v_pk_add_f32 v[212:213], v[110:111], v[212:213]
	v_pk_add_f32 v[100:101], v[100:101], v[104:105]
	v_pk_add_f32 v[212:213], v[212:213], v[100:101]
	v_add_f32_e32 v212, v212, v213
	s_nop 1
	v_add_f32_dpp v212, v212, v212 quad_perm:[1,0,3,2] row_mask:0xf bank_mask:0xf
	s_nop 1
	v_add_f32_dpp v212, v212, v212 quad_perm:[2,3,0,1] row_mask:0xf bank_mask:0xf
	s_nop 1
	v_add_f32_dpp v212, v212, v212 row_half_mirror row_mask:0xf bank_mask:0xf
	s_nop 1
	v_add_f32_dpp v212, v212, v212 row_ror:8 row_mask:0xf bank_mask:0xf
	v_mov_b32_e32 v213, v212
	s_nop 1
	v_permlane16_swap_b32_e32 v213, v212
	v_add_f32_e32 v212, v212, v213
	v_mov_b32_e32 v213, v212
	s_nop 1
	v_permlane32_swap_b32_e32 v213, v212
	v_add_f32_e32 v212, v212, v213
	v_fmamk_f32 v212, v212, 0x3a800000, v49
	v_mul_f32_e32 v213, 0x4f800000, v212
	v_cmp_gt_f32_e32 vcc, s8, v212
	s_nop 1
	v_cndmask_b32_e32 v212, v212, v213, vcc
	v_sqrt_f32_e32 v213, v212
	s_nop 0
	v_add_u32_e32 v97, -1, v213
	v_fma_f32 v100, -v97, v213, v212
	v_cmp_ge_f32_e64 s[0:1], 0, v100
	v_add_u32_e32 v100, 1, v213
	s_nop 0
	v_cndmask_b32_e64 v97, v213, v97, s[0:1]
	v_fma_f32 v213, -v100, v213, v212
	v_cmp_lt_f32_e64 s[0:1], 0, v213
	s_nop 1
	v_cndmask_b32_e64 v213, v97, v100, s[0:1]
	v_mul_f32_e32 v97, 0x37800000, v213
	v_cndmask_b32_e32 v213, v213, v97, vcc
	v_cmp_class_f32_e32 vcc, v212, v92
	s_nop 1
	v_cndmask_b32_e32 v212, v213, v212, vcc
	v_div_scale_f32 v213, s[0:1], v212, v212, 1.0
	v_rcp_f32_e32 v97, v213
	s_nop 0
	v_fma_f32 v100, -v213, v97, 1.0
	v_fmac_f32_e32 v97, v100, v97
	v_div_scale_f32 v100, vcc, 1.0, v212, 1.0
	v_mul_f32_e32 v101, v100, v97
	v_fma_f32 v104, -v213, v101, v100
	v_fmac_f32_e32 v101, v104, v97
	v_fma_f32 v213, -v213, v101, v100
	v_div_fmas_f32 v213, v213, v97, v101
	v_div_fixup_f32 v100, v213, v212, 1.0
	v_mov_b32_e32 v212, v214
	v_mov_b32_e32 v213, v208
	v_mov_b32_e32 v208, v215
	v_pk_mul_f32 v[212:213], v[100:101], v[212:213] op_sel_hi:[0,1]
	v_pk_mul_f32 v[214:215], v[100:101], v[208:209] op_sel_hi:[0,1]
	v_mov_b32_e32 v208, v102
	v_mov_b32_e32 v209, v210
	v_mov_b32_e32 v210, v103
	v_pk_fma_f32 v[214:215], v[70:71], v[214:215], v[22:23]
	v_pk_fma_f32 v[212:213], v[72:73], v[212:213], v[20:21]
	v_pk_mul_f32 v[208:209], v[100:101], v[208:209] op_sel_hi:[0,1]
	v_pk_mul_f32 v[210:211], v[100:101], v[210:211] op_sel_hi:[0,1]
	s_mov_b64 s[6:7], 0x1800
	v_lshl_add_u64 v[104:105], s[6:7], 1, v[68:69]
	v_pk_fma_f32 v[210:211], v[74:75], v[210:211], v[18:19]
	v_pk_fma_f32 v[208:209], v[76:77], v[208:209], v[16:17]
	v_cvt_pk_bf16_f32 v212, v212, v213
	v_cvt_pk_bf16_f32 v213, v214, v215
	v_mov_b32_e32 v97, v61
	v_cvt_pk_bf16_f32 v214, v208, v209
	v_cvt_pk_bf16_f32 v215, v210, v211
	global_store_dwordx4 v[104:105], v[212:215], off
	v_pk_mul_f32 v[208:209], v[96:97], v[100:101] op_sel_hi:[1,0]
	v_pk_mul_f32 v[210:211], v[98:99], v[100:101] op_sel_hi:[1,0]
	v_pk_mul_f32 v[212:213], v[94:95], v[100:101] op_sel_hi:[1,0]
	v_pk_mul_f32 v[214:215], v[108:109], v[100:101] op_sel_hi:[1,0]
	v_pk_fma_f32 v[212:213], v[80:81], v[212:213], v[28:29]
	v_pk_fma_f32 v[214:215], v[78:79], v[214:215], v[30:31]
	v_pk_fma_f32 v[210:211], v[82:83], v[210:211], v[26:27]
	v_pk_fma_f32 v[208:209], v[84:85], v[208:209], v[24:25]
	v_cvt_pk_bf16_f32 v212, v212, v213
	v_cvt_pk_bf16_f32 v213, v214, v215
	s_nop 0
	v_cvt_pk_bf16_f32 v214, v208, v209
	v_cvt_pk_bf16_f32 v215, v210, v211
	global_store_dwordx4 v[104:105], v[212:215], off offset:1024
	s_nop 0
	s_nop 0
	s_nop 0
	s_nop 0
	s_nop 0
	s_nop 0
	s_nop 0
	s_nop 0
	s_waitcnt vmcnt(14)
	v_lshlrev_b32_e32 v96, 16, v222
	v_and_b32_e32 v61, 0xffff0000, v222
	v_lshlrev_b32_e32 v98, 16, v223
	v_and_b32_e32 v99, 0xffff0000, v223
	v_lshlrev_b32_e32 v223, 16, v217
	v_lshlrev_b32_e32 v222, 16, v216
	v_and_b32_e32 v217, 0xffff0000, v217
	v_and_b32_e32 v216, 0xffff0000, v216
	v_lshlrev_b32_e32 v103, 16, v219
	v_lshlrev_b32_e32 v102, 16, v218
	v_and_b32_e32 v219, 0xffff0000, v219
	v_and_b32_e32 v218, 0xffff0000, v218
	v_lshlrev_b32_e32 v94, 16, v220
	v_and_b32_e32 v95, 0xffff0000, v220
	v_pk_mul_f32 v[100:101], v[216:217], v[216:217]
	v_pk_mul_f32 v[104:105], v[218:219], v[218:219]
	v_lshlrev_b32_e32 v108, 16, v221
	v_pk_fma_f32 v[100:101], v[222:223], v[222:223], v[100:101]
	v_pk_fma_f32 v[104:105], v[102:103], v[102:103], v[104:105]
	v_mul_f32_e32 v97, v94, v94
	v_mul_f32_e32 v107, v95, v95
	v_and_b32_e32 v109, 0xffff0000, v221
	v_mul_f32_e32 v220, v108, v108
	v_mov_b32_e32 v106, v96
	v_pk_add_f32 v[100:101], v[100:101], v[100:101] op_sel_hi:[0,1]
	v_pk_add_f32 v[104:105], v[104:105], v[104:105] op_sel_hi:[0,1]
	v_pk_fma_f32 v[220:221], v[108:109], v[108:109], v[220:221] op_sel_hi:[1,1,0]
	v_pk_add_f32 v[106:107], v[96:97], v[106:107]
	v_mul_f32_e32 v220, v61, v61
	v_mul_f32_e32 v100, v98, v98
	v_mul_f32_e32 v104, v99, v99
	v_mul_f32_e32 v110, v96, v96
	v_mov_b32_e32 v111, v107
	v_pk_add_f32 v[220:221], v[110:111], v[220:221]
	v_pk_add_f32 v[100:101], v[100:101], v[104:105]
	v_pk_add_f32 v[220:221], v[220:221], v[100:101]
	v_add_f32_e32 v220, v220, v221
	s_nop 1
	v_add_f32_dpp v220, v220, v220 quad_perm:[1,0,3,2] row_mask:0xf bank_mask:0xf
	s_nop 1
	v_add_f32_dpp v220, v220, v220 quad_perm:[2,3,0,1] row_mask:0xf bank_mask:0xf
	s_nop 1
	v_add_f32_dpp v220, v220, v220 row_half_mirror row_mask:0xf bank_mask:0xf
	s_nop 1
	v_add_f32_dpp v220, v220, v220 row_ror:8 row_mask:0xf bank_mask:0xf
	v_mov_b32_e32 v221, v220
	s_nop 1
	v_permlane16_swap_b32_e32 v221, v220
	v_add_f32_e32 v220, v220, v221
	v_mov_b32_e32 v221, v220
	s_nop 1
	v_permlane32_swap_b32_e32 v221, v220
	v_add_f32_e32 v220, v220, v221
	v_fmamk_f32 v220, v220, 0x3a800000, v49
	v_mul_f32_e32 v221, 0x4f800000, v220
	v_cmp_gt_f32_e32 vcc, s8, v220
	s_nop 1
	v_cndmask_b32_e32 v220, v220, v221, vcc
	v_sqrt_f32_e32 v221, v220
	s_nop 0
	v_add_u32_e32 v97, -1, v221
	v_fma_f32 v100, -v97, v221, v220
	v_cmp_ge_f32_e64 s[0:1], 0, v100
	v_add_u32_e32 v100, 1, v221
	s_nop 0
	v_cndmask_b32_e64 v97, v221, v97, s[0:1]
	v_fma_f32 v221, -v100, v221, v220
	v_cmp_lt_f32_e64 s[0:1], 0, v221
	s_nop 1
	v_cndmask_b32_e64 v221, v97, v100, s[0:1]
	v_mul_f32_e32 v97, 0x37800000, v221
	v_cndmask_b32_e32 v221, v221, v97, vcc
	v_cmp_class_f32_e32 vcc, v220, v92
	s_nop 1
	v_cndmask_b32_e32 v220, v221, v220, vcc
	v_div_scale_f32 v221, s[0:1], v220, v220, 1.0
	v_rcp_f32_e32 v97, v221
	s_nop 0
	v_fma_f32 v100, -v221, v97, 1.0
	v_fmac_f32_e32 v97, v100, v97
	v_div_scale_f32 v100, vcc, 1.0, v220, 1.0
	v_mul_f32_e32 v101, v100, v97
	v_fma_f32 v104, -v221, v101, v100
	v_fmac_f32_e32 v101, v104, v97
	v_fma_f32 v221, -v221, v101, v100
	v_div_fmas_f32 v221, v221, v97, v101
	v_div_fixup_f32 v100, v221, v220, 1.0
	v_mov_b32_e32 v220, v222
	v_mov_b32_e32 v221, v216
	v_mov_b32_e32 v216, v223
	v_pk_mul_f32 v[220:221], v[100:101], v[220:221] op_sel_hi:[0,1]
	v_pk_mul_f32 v[222:223], v[100:101], v[216:217] op_sel_hi:[0,1]
	v_mov_b32_e32 v216, v102
	v_mov_b32_e32 v217, v218
	v_mov_b32_e32 v218, v103
	v_pk_fma_f32 v[222:223], v[70:71], v[222:223], v[22:23]
	v_pk_fma_f32 v[220:221], v[72:73], v[220:221], v[20:21]
	v_pk_mul_f32 v[216:217], v[100:101], v[216:217] op_sel_hi:[0,1]
	v_pk_mul_f32 v[218:219], v[100:101], v[218:219] op_sel_hi:[0,1]
	s_mov_b64 s[6:7], 0x1c00
	v_lshl_add_u64 v[104:105], s[6:7], 1, v[68:69]
	v_pk_fma_f32 v[218:219], v[74:75], v[218:219], v[18:19]
	v_pk_fma_f32 v[216:217], v[76:77], v[216:217], v[16:17]
	v_cvt_pk_bf16_f32 v220, v220, v221
	v_cvt_pk_bf16_f32 v221, v222, v223
	v_mov_b32_e32 v97, v61
	v_cvt_pk_bf16_f32 v222, v216, v217
	v_cvt_pk_bf16_f32 v223, v218, v219
	global_store_dwordx4 v[104:105], v[220:223], off
	v_pk_mul_f32 v[216:217], v[96:97], v[100:101] op_sel_hi:[1,0]
	v_pk_mul_f32 v[218:219], v[98:99], v[100:101] op_sel_hi:[1,0]
	v_pk_mul_f32 v[220:221], v[94:95], v[100:101] op_sel_hi:[1,0]
	v_pk_mul_f32 v[222:223], v[108:109], v[100:101] op_sel_hi:[1,0]
	v_pk_fma_f32 v[220:221], v[80:81], v[220:221], v[28:29]
	v_pk_fma_f32 v[222:223], v[78:79], v[222:223], v[30:31]
	v_pk_fma_f32 v[218:219], v[82:83], v[218:219], v[26:27]
	v_pk_fma_f32 v[216:217], v[84:85], v[216:217], v[24:25]
	v_cvt_pk_bf16_f32 v220, v220, v221
	v_cvt_pk_bf16_f32 v221, v222, v223
	s_nop 0
	v_cvt_pk_bf16_f32 v222, v216, v217
	v_cvt_pk_bf16_f32 v223, v218, v219
	global_store_dwordx4 v[104:105], v[220:223], off offset:1024
	s_nop 0
	s_nop 0
	s_nop 0
	s_nop 0
	s_nop 0
	s_nop 0
	s_nop 0
	s_nop 0
	s_branch .LBB0_494

.LBB0_1145:
	v_lshrrev_b32_e32 v16, 8, v93
	v_mul_hi_i32_i24_e32 v17, 0x9000, v16
	v_mul_i32_i24_e32 v16, 0x9000, v16
	v_lshl_add_u64 v[16:17], s[96:97], 0, v[16:17]
	v_lshl_add_u64 v[18:19], v[16:17], 0, s[14:15]
	v_lshl_add_u64 v[24:25], v[16:17], 0, s[16:17]
	v_lshl_add_u64 v[16:17], v[18:19], 0, v[52:53]
	v_lshl_add_u64 v[26:27], v[24:25], 0, v[52:53]
	v_lshl_add_u64 v[28:29], v[18:19], 0, v[62:63]
	v_lshl_add_u64 v[32:33], v[24:25], 0, v[62:63]
	global_load_dwordx4 v[76:79], v[56:57], off offset:16
	global_load_dwordx4 v[72:75], v[56:57], off
	global_load_dwordx4 v[80:83], v[16:17], off offset:16
	global_load_dwordx4 v[94:97], v[16:17], off
	global_load_dwordx4 v[98:101], v[28:29], off offset:16
	global_load_dwordx4 v[102:105], v[28:29], off
	s_nop 0
	global_load_dwordx4 v[16:19], v[26:27], off offset:16
	global_load_dwordx4 v[20:23], v[26:27], off
	global_load_dwordx4 v[106:109], v[56:57], off offset:2064
	global_load_dwordx4 v[110:113], v[56:57], off offset:2048
	s_nop 0
	global_load_dwordx4 v[24:27], v[32:33], off offset:16
	global_load_dwordx4 v[28:31], v[32:33], off
	v_lshlrev_b32_e32 v32, 3, v93
	v_ashrrev_i32_e32 v33, 31, v32
	v_lshlrev_b64 v[68:69], 11, v[32:33]
	v_lshl_add_u64 v[32:33], s[22:23], 0, v[68:69]
	v_lshl_add_u64 v[32:33], v[32:33], 0, v[64:65]
	global_load_dwordx4 v[44:47], v[32:33], off
	global_load_dwordx4 v[40:43], v[32:33], off offset:1024
	v_ashrrev_i32_e32 v61, 31, v60
	v_lshlrev_b64 v[66:67], 11, v[60:61]
	v_lshl_add_u64 v[66:67], v[58:59], 0, v[66:67]
	v_lshl_add_u64 v[68:69], v[54:55], 0, v[68:69]
	s_mov_b64 s[6:7], 0xc500800
	v_lshl_add_u64 v[226:227], v[66:67], 0, s[6:7]
	global_load_dwordx4 v[32:35], v[226:227], off
	global_load_dwordx4 v[36:39], v[226:227], off offset:1024
	s_mov_b64 s[6:7], 0xc501000
	v_lshl_add_u64 v[224:225], v[66:67], 0, s[6:7]
	global_load_dwordx4 v[176:179], v[224:225], off
	global_load_dwordx4 v[180:183], v[224:225], off offset:1024
	s_mov_b64 s[6:7], 0xc501800
	v_lshl_add_u64 v[226:227], v[66:67], 0, s[6:7]
	global_load_dwordx4 v[184:187], v[226:227], off
	global_load_dwordx4 v[188:191], v[226:227], off offset:1024
	s_mov_b64 s[6:7], 0xc502000
	v_lshl_add_u64 v[224:225], v[66:67], 0, s[6:7]
	global_load_dwordx4 v[192:195], v[224:225], off
	global_load_dwordx4 v[196:199], v[224:225], off offset:1024
	s_mov_b64 s[6:7], 0xc502800
	v_lshl_add_u64 v[226:227], v[66:67], 0, s[6:7]
	global_load_dwordx4 v[200:203], v[226:227], off
	global_load_dwordx4 v[204:207], v[226:227], off offset:1024
	s_mov_b64 s[6:7], 0xc503000
	v_lshl_add_u64 v[224:225], v[66:67], 0, s[6:7]
	global_load_dwordx4 v[208:211], v[224:225], off
	global_load_dwordx4 v[212:215], v[224:225], off offset:1024
	s_mov_b64 s[6:7], 0xc503800
	v_lshl_add_u64 v[226:227], v[66:67], 0, s[6:7]
	global_load_dwordx4 v[216:219], v[226:227], off
	global_load_dwordx4 v[220:223], v[226:227], off offset:1024
	s_waitcnt vmcnt(16)
	v_pk_add_f32 v[100:101], v[100:101], 1.0 op_sel_hi:[1,0]
	v_pk_add_f32 v[98:99], v[98:99], 1.0 op_sel_hi:[1,0]
	v_pk_add_f32 v[82:83], v[82:83], 1.0 op_sel_hi:[1,0]
	v_pk_add_f32 v[70:71], v[96:97], 1.0 op_sel_hi:[1,0]
	v_pk_add_f32 v[84:85], v[94:95], 1.0 op_sel_hi:[1,0]
	v_pk_add_f32 v[80:81], v[80:81], 1.0 op_sel_hi:[1,0]
	v_pk_add_f32 v[94:95], v[104:105], 1.0 op_sel_hi:[1,0]
	v_pk_add_f32 v[96:97], v[102:103], 1.0 op_sel_hi:[1,0]
	v_pk_mul_f32 v[70:71], v[74:75], v[70:71]
	v_pk_mul_f32 v[72:73], v[72:73], v[84:85]
	v_pk_mul_f32 v[74:75], v[78:79], v[82:83]
	v_pk_mul_f32 v[76:77], v[76:77], v[80:81]
	v_pk_mul_f32 v[78:79], v[112:113], v[94:95]
	v_pk_mul_f32 v[80:81], v[110:111], v[96:97]
	v_pk_mul_f32 v[82:83], v[108:109], v[100:101]
	v_pk_mul_f32 v[84:85], v[106:107], v[98:99]
	s_waitcnt vmcnt(14)
	v_lshlrev_b32_e32 v96, 16, v42
	v_and_b32_e32 v61, 0xffff0000, v42
	v_lshlrev_b32_e32 v98, 16, v43
	v_and_b32_e32 v99, 0xffff0000, v43
	v_lshlrev_b32_e32 v43, 16, v45
	v_lshlrev_b32_e32 v42, 16, v44
	v_and_b32_e32 v45, 0xffff0000, v45
	v_and_b32_e32 v44, 0xffff0000, v44
	v_lshlrev_b32_e32 v103, 16, v47
	v_lshlrev_b32_e32 v102, 16, v46
	v_and_b32_e32 v47, 0xffff0000, v47
	v_and_b32_e32 v46, 0xffff0000, v46
	v_lshlrev_b32_e32 v94, 16, v40
	v_and_b32_e32 v95, 0xffff0000, v40
	v_pk_mul_f32 v[100:101], v[44:45], v[44:45]
	v_pk_mul_f32 v[104:105], v[46:47], v[46:47]
	v_lshlrev_b32_e32 v108, 16, v41
	v_pk_fma_f32 v[100:101], v[42:43], v[42:43], v[100:101]
	v_pk_fma_f32 v[104:105], v[102:103], v[102:103], v[104:105]
	v_mul_f32_e32 v97, v94, v94
	v_mul_f32_e32 v107, v95, v95
	v_and_b32_e32 v109, 0xffff0000, v41
	v_mul_f32_e32 v40, v108, v108
	v_mov_b32_e32 v106, v96
	v_pk_add_f32 v[100:101], v[100:101], v[100:101] op_sel_hi:[0,1]
	v_pk_add_f32 v[104:105], v[104:105], v[104:105] op_sel_hi:[0,1]
	v_pk_fma_f32 v[40:41], v[108:109], v[108:109], v[40:41] op_sel_hi:[1,1,0]
	v_pk_add_f32 v[106:107], v[96:97], v[106:107]
	v_mul_f32_e32 v40, v61, v61
	v_mul_f32_e32 v100, v98, v98
	v_mul_f32_e32 v104, v99, v99
	v_mul_f32_e32 v110, v96, v96
	v_mov_b32_e32 v111, v107
	v_pk_add_f32 v[40:41], v[110:111], v[40:41]
	v_pk_add_f32 v[100:101], v[100:101], v[104:105]
	v_pk_add_f32 v[40:41], v[40:41], v[100:101]
	v_add_f32_e32 v40, v40, v41
	s_nop 1
	v_add_f32_dpp v40, v40, v40 quad_perm:[1,0,3,2] row_mask:0xf bank_mask:0xf
	s_nop 1
	v_add_f32_dpp v40, v40, v40 quad_perm:[2,3,0,1] row_mask:0xf bank_mask:0xf
	s_nop 1
	v_add_f32_dpp v40, v40, v40 row_half_mirror row_mask:0xf bank_mask:0xf
	s_nop 1
	v_add_f32_dpp v40, v40, v40 row_ror:8 row_mask:0xf bank_mask:0xf
	v_mov_b32_e32 v41, v40
	s_nop 1
	v_permlane16_swap_b32_e32 v41, v40
	v_add_f32_e32 v40, v40, v41
	v_mov_b32_e32 v41, v40
	s_nop 1
	v_permlane32_swap_b32_e32 v41, v40
	v_add_f32_e32 v40, v40, v41
	v_fmamk_f32 v40, v40, 0x3a800000, v49
	v_mul_f32_e32 v41, 0x4f800000, v40
	v_cmp_gt_f32_e32 vcc, s9, v40
	s_nop 1
	v_cndmask_b32_e32 v40, v40, v41, vcc
	v_sqrt_f32_e32 v41, v40
	s_nop 0
	v_add_u32_e32 v97, -1, v41
	v_fma_f32 v100, -v97, v41, v40
	v_cmp_ge_f32_e64 s[0:1], 0, v100
	v_add_u32_e32 v100, 1, v41
	s_nop 0
	v_cndmask_b32_e64 v97, v41, v97, s[0:1]
	v_fma_f32 v41, -v100, v41, v40
	v_cmp_lt_f32_e64 s[0:1], 0, v41
	s_nop 1
	v_cndmask_b32_e64 v41, v97, v100, s[0:1]
	v_mul_f32_e32 v97, 0x37800000, v41
	v_cndmask_b32_e32 v41, v41, v97, vcc
	v_cmp_class_f32_e32 vcc, v40, v92
	s_nop 1
	v_cndmask_b32_e32 v40, v41, v40, vcc
	v_div_scale_f32 v41, s[0:1], v40, v40, 1.0
	v_rcp_f32_e32 v97, v41
	s_nop 0
	v_fma_f32 v100, -v41, v97, 1.0
	v_fmac_f32_e32 v97, v100, v97
	v_div_scale_f32 v100, vcc, 1.0, v40, 1.0
	v_mul_f32_e32 v101, v100, v97
	v_fma_f32 v104, -v41, v101, v100
	v_fmac_f32_e32 v101, v104, v97
	v_fma_f32 v41, -v41, v101, v100
	v_div_fmas_f32 v41, v41, v97, v101
	v_div_fixup_f32 v100, v41, v40, 1.0
	v_mov_b32_e32 v40, v42
	v_mov_b32_e32 v41, v44
	v_mov_b32_e32 v44, v43
	v_pk_mul_f32 v[40:41], v[100:101], v[40:41] op_sel_hi:[0,1]
	v_pk_mul_f32 v[42:43], v[100:101], v[44:45] op_sel_hi:[0,1]
	v_mov_b32_e32 v44, v102
	v_mov_b32_e32 v45, v46
	v_mov_b32_e32 v46, v103
	v_pk_fma_f32 v[42:43], v[70:71], v[42:43], v[22:23]
	v_pk_fma_f32 v[40:41], v[72:73], v[40:41], v[20:21]
	v_pk_mul_f32 v[44:45], v[100:101], v[44:45] op_sel_hi:[0,1]
	v_pk_mul_f32 v[46:47], v[100:101], v[46:47] op_sel_hi:[0,1]
	s_mov_b64 s[6:7], 0x0
	v_lshl_add_u64 v[104:105], s[6:7], 1, v[68:69]
	v_pk_fma_f32 v[46:47], v[74:75], v[46:47], v[18:19]
	v_pk_fma_f32 v[44:45], v[76:77], v[44:45], v[16:17]
	v_cvt_pk_bf16_f32 v40, v40, v41
	v_cvt_pk_bf16_f32 v41, v42, v43
	v_mov_b32_e32 v97, v61
	v_cvt_pk_bf16_f32 v42, v44, v45
	v_cvt_pk_bf16_f32 v43, v46, v47
	global_store_dwordx4 v[104:105], v[40:43], off
	v_pk_mul_f32 v[44:45], v[96:97], v[100:101] op_sel_hi:[1,0]
	v_pk_mul_f32 v[46:47], v[98:99], v[100:101] op_sel_hi:[1,0]
	v_pk_mul_f32 v[40:41], v[94:95], v[100:101] op_sel_hi:[1,0]
	v_pk_mul_f32 v[42:43], v[108:109], v[100:101] op_sel_hi:[1,0]
	v_pk_fma_f32 v[40:41], v[80:81], v[40:41], v[28:29]
	v_pk_fma_f32 v[42:43], v[78:79], v[42:43], v[30:31]
	v_pk_fma_f32 v[46:47], v[82:83], v[46:47], v[26:27]
	v_pk_fma_f32 v[44:45], v[84:85], v[44:45], v[24:25]
	v_cvt_pk_bf16_f32 v40, v40, v41
	v_cvt_pk_bf16_f32 v41, v42, v43
	s_nop 0
	v_cvt_pk_bf16_f32 v42, v44, v45
	v_cvt_pk_bf16_f32 v43, v46, v47
	global_store_dwordx4 v[104:105], v[40:43], off offset:1024
	s_nop 0
	s_nop 0
	s_nop 0
	s_nop 0
	s_nop 0
	s_nop 0
	s_nop 0
	s_nop 0
	s_waitcnt vmcnt(14)
	v_lshlrev_b32_e32 v96, 16, v38
	v_and_b32_e32 v61, 0xffff0000, v38
	v_lshlrev_b32_e32 v98, 16, v39
	v_and_b32_e32 v99, 0xffff0000, v39
	v_lshlrev_b32_e32 v39, 16, v33
	v_lshlrev_b32_e32 v38, 16, v32
	v_and_b32_e32 v33, 0xffff0000, v33
	v_and_b32_e32 v32, 0xffff0000, v32
	v_lshlrev_b32_e32 v103, 16, v35
	v_lshlrev_b32_e32 v102, 16, v34
	v_and_b32_e32 v35, 0xffff0000, v35
	v_and_b32_e32 v34, 0xffff0000, v34
	v_lshlrev_b32_e32 v94, 16, v36
	v_and_b32_e32 v95, 0xffff0000, v36
	v_pk_mul_f32 v[100:101], v[32:33], v[32:33]
	v_pk_mul_f32 v[104:105], v[34:35], v[34:35]
	v_lshlrev_b32_e32 v108, 16, v37
	v_pk_fma_f32 v[100:101], v[38:39], v[38:39], v[100:101]
	v_pk_fma_f32 v[104:105], v[102:103], v[102:103], v[104:105]
	v_mul_f32_e32 v97, v94, v94
	v_mul_f32_e32 v107, v95, v95
	v_and_b32_e32 v109, 0xffff0000, v37
	v_mul_f32_e32 v36, v108, v108
	v_mov_b32_e32 v106, v96
	v_pk_add_f32 v[100:101], v[100:101], v[100:101] op_sel_hi:[0,1]
	v_pk_add_f32 v[104:105], v[104:105], v[104:105] op_sel_hi:[0,1]
	v_pk_fma_f32 v[36:37], v[108:109], v[108:109], v[36:37] op_sel_hi:[1,1,0]
	v_pk_add_f32 v[106:107], v[96:97], v[106:107]
	v_mul_f32_e32 v36, v61, v61
	v_mul_f32_e32 v100, v98, v98
	v_mul_f32_e32 v104, v99, v99
	v_mul_f32_e32 v110, v96, v96
	v_mov_b32_e32 v111, v107
	v_pk_add_f32 v[36:37], v[110:111], v[36:37]
	v_pk_add_f32 v[100:101], v[100:101], v[104:105]
	v_pk_add_f32 v[36:37], v[36:37], v[100:101]
	v_add_f32_e32 v36, v36, v37
	s_nop 1
	v_add_f32_dpp v36, v36, v36 quad_perm:[1,0,3,2] row_mask:0xf bank_mask:0xf
	s_nop 1
	v_add_f32_dpp v36, v36, v36 quad_perm:[2,3,0,1] row_mask:0xf bank_mask:0xf
	s_nop 1
	v_add_f32_dpp v36, v36, v36 row_half_mirror row_mask:0xf bank_mask:0xf
	s_nop 1
	v_add_f32_dpp v36, v36, v36 row_ror:8 row_mask:0xf bank_mask:0xf
	v_mov_b32_e32 v37, v36
	s_nop 1
	v_permlane16_swap_b32_e32 v37, v36
	v_add_f32_e32 v36, v36, v37
	v_mov_b32_e32 v37, v36
	s_nop 1
	v_permlane32_swap_b32_e32 v37, v36
	v_add_f32_e32 v36, v36, v37
	v_fmamk_f32 v36, v36, 0x3a800000, v49
	v_mul_f32_e32 v37, 0x4f800000, v36
	v_cmp_gt_f32_e32 vcc, s9, v36
	s_nop 1
	v_cndmask_b32_e32 v36, v36, v37, vcc
	v_sqrt_f32_e32 v37, v36
	s_nop 0
	v_add_u32_e32 v97, -1, v37
	v_fma_f32 v100, -v97, v37, v36
	v_cmp_ge_f32_e64 s[0:1], 0, v100
	v_add_u32_e32 v100, 1, v37
	s_nop 0
	v_cndmask_b32_e64 v97, v37, v97, s[0:1]
	v_fma_f32 v37, -v100, v37, v36
	v_cmp_lt_f32_e64 s[0:1], 0, v37
	s_nop 1
	v_cndmask_b32_e64 v37, v97, v100, s[0:1]
	v_mul_f32_e32 v97, 0x37800000, v37
	v_cndmask_b32_e32 v37, v37, v97, vcc
	v_cmp_class_f32_e32 vcc, v36, v92
	s_nop 1
	v_cndmask_b32_e32 v36, v37, v36, vcc
	v_div_scale_f32 v37, s[0:1], v36, v36, 1.0
	v_rcp_f32_e32 v97, v37
	s_nop 0
	v_fma_f32 v100, -v37, v97, 1.0
	v_fmac_f32_e32 v97, v100, v97
	v_div_scale_f32 v100, vcc, 1.0, v36, 1.0
	v_mul_f32_e32 v101, v100, v97
	v_fma_f32 v104, -v37, v101, v100
	v_fmac_f32_e32 v101, v104, v97
	v_fma_f32 v37, -v37, v101, v100
	v_div_fmas_f32 v37, v37, v97, v101
	v_div_fixup_f32 v100, v37, v36, 1.0
	v_mov_b32_e32 v36, v38
	v_mov_b32_e32 v37, v32
	v_mov_b32_e32 v32, v39
	v_pk_mul_f32 v[36:37], v[100:101], v[36:37] op_sel_hi:[0,1]
	v_pk_mul_f32 v[38:39], v[100:101], v[32:33] op_sel_hi:[0,1]
	v_mov_b32_e32 v32, v102
	v_mov_b32_e32 v33, v34
	v_mov_b32_e32 v34, v103
	v_pk_fma_f32 v[38:39], v[70:71], v[38:39], v[22:23]
	v_pk_fma_f32 v[36:37], v[72:73], v[36:37], v[20:21]
	v_pk_mul_f32 v[32:33], v[100:101], v[32:33] op_sel_hi:[0,1]
	v_pk_mul_f32 v[34:35], v[100:101], v[34:35] op_sel_hi:[0,1]
	s_mov_b64 s[6:7], 0x400
	v_lshl_add_u64 v[104:105], s[6:7], 1, v[68:69]
	v_pk_fma_f32 v[34:35], v[74:75], v[34:35], v[18:19]
	v_pk_fma_f32 v[32:33], v[76:77], v[32:33], v[16:17]
	v_cvt_pk_bf16_f32 v36, v36, v37
	v_cvt_pk_bf16_f32 v37, v38, v39
	v_mov_b32_e32 v97, v61
	v_cvt_pk_bf16_f32 v38, v32, v33
	v_cvt_pk_bf16_f32 v39, v34, v35
	global_store_dwordx4 v[104:105], v[36:39], off
	v_pk_mul_f32 v[32:33], v[96:97], v[100:101] op_sel_hi:[1,0]
	v_pk_mul_f32 v[34:35], v[98:99], v[100:101] op_sel_hi:[1,0]
	v_pk_mul_f32 v[36:37], v[94:95], v[100:101] op_sel_hi:[1,0]
	v_pk_mul_f32 v[38:39], v[108:109], v[100:101] op_sel_hi:[1,0]
	v_pk_fma_f32 v[36:37], v[80:81], v[36:37], v[28:29]
	v_pk_fma_f32 v[38:39], v[78:79], v[38:39], v[30:31]
	v_pk_fma_f32 v[34:35], v[82:83], v[34:35], v[26:27]
	v_pk_fma_f32 v[32:33], v[84:85], v[32:33], v[24:25]
	v_cvt_pk_bf16_f32 v36, v36, v37
	v_cvt_pk_bf16_f32 v37, v38, v39
	s_nop 0
	v_cvt_pk_bf16_f32 v38, v32, v33
	v_cvt_pk_bf16_f32 v39, v34, v35
	global_store_dwordx4 v[104:105], v[36:39], off offset:1024
	s_nop 0
	s_nop 0
	s_nop 0
	s_nop 0
	s_nop 0
	s_nop 0
	s_nop 0
	s_nop 0
	s_waitcnt vmcnt(14)
	v_lshlrev_b32_e32 v96, 16, v182
	v_and_b32_e32 v61, 0xffff0000, v182
	v_lshlrev_b32_e32 v98, 16, v183
	v_and_b32_e32 v99, 0xffff0000, v183
	v_lshlrev_b32_e32 v183, 16, v177
	v_lshlrev_b32_e32 v182, 16, v176
	v_and_b32_e32 v177, 0xffff0000, v177
	v_and_b32_e32 v176, 0xffff0000, v176
	v_lshlrev_b32_e32 v103, 16, v179
	v_lshlrev_b32_e32 v102, 16, v178
	v_and_b32_e32 v179, 0xffff0000, v179
	v_and_b32_e32 v178, 0xffff0000, v178
	v_lshlrev_b32_e32 v94, 16, v180
	v_and_b32_e32 v95, 0xffff0000, v180
	v_pk_mul_f32 v[100:101], v[176:177], v[176:177]
	v_pk_mul_f32 v[104:105], v[178:179], v[178:179]
	v_lshlrev_b32_e32 v108, 16, v181
	v_pk_fma_f32 v[100:101], v[182:183], v[182:183], v[100:101]
	v_pk_fma_f32 v[104:105], v[102:103], v[102:103], v[104:105]
	v_mul_f32_e32 v97, v94, v94
	v_mul_f32_e32 v107, v95, v95
	v_and_b32_e32 v109, 0xffff0000, v181
	v_mul_f32_e32 v180, v108, v108
	v_mov_b32_e32 v106, v96
	v_pk_add_f32 v[100:101], v[100:101], v[100:101] op_sel_hi:[0,1]
	v_pk_add_f32 v[104:105], v[104:105], v[104:105] op_sel_hi:[0,1]
	v_pk_fma_f32 v[180:181], v[108:109], v[108:109], v[180:181] op_sel_hi:[1,1,0]
	v_pk_add_f32 v[106:107], v[96:97], v[106:107]
	v_mul_f32_e32 v180, v61, v61
	v_mul_f32_e32 v100, v98, v98
	v_mul_f32_e32 v104, v99, v99
	v_mul_f32_e32 v110, v96, v96
	v_mov_b32_e32 v111, v107
	v_pk_add_f32 v[180:181], v[110:111], v[180:181]
	v_pk_add_f32 v[100:101], v[100:101], v[104:105]
	v_pk_add_f32 v[180:181], v[180:181], v[100:101]
	v_add_f32_e32 v180, v180, v181
	s_nop 1
	v_add_f32_dpp v180, v180, v180 quad_perm:[1,0,3,2] row_mask:0xf bank_mask:0xf
	s_nop 1
	v_add_f32_dpp v180, v180, v180 quad_perm:[2,3,0,1] row_mask:0xf bank_mask:0xf
	s_nop 1
	v_add_f32_dpp v180, v180, v180 row_half_mirror row_mask:0xf bank_mask:0xf
	s_nop 1
	v_add_f32_dpp v180, v180, v180 row_ror:8 row_mask:0xf bank_mask:0xf
	v_mov_b32_e32 v181, v180
	s_nop 1
	v_permlane16_swap_b32_e32 v181, v180
	v_add_f32_e32 v180, v180, v181
	v_mov_b32_e32 v181, v180
	s_nop 1
	v_permlane32_swap_b32_e32 v181, v180
	v_add_f32_e32 v180, v180, v181
	v_fmamk_f32 v180, v180, 0x3a800000, v49
	v_mul_f32_e32 v181, 0x4f800000, v180
	v_cmp_gt_f32_e32 vcc, s9, v180
	s_nop 1
	v_cndmask_b32_e32 v180, v180, v181, vcc
	v_sqrt_f32_e32 v181, v180
	s_nop 0
	v_add_u32_e32 v97, -1, v181
	v_fma_f32 v100, -v97, v181, v180
	v_cmp_ge_f32_e64 s[0:1], 0, v100
	v_add_u32_e32 v100, 1, v181
	s_nop 0
	v_cndmask_b32_e64 v97, v181, v97, s[0:1]
	v_fma_f32 v181, -v100, v181, v180
	v_cmp_lt_f32_e64 s[0:1], 0, v181
	s_nop 1
	v_cndmask_b32_e64 v181, v97, v100, s[0:1]
	v_mul_f32_e32 v97, 0x37800000, v181
	v_cndmask_b32_e32 v181, v181, v97, vcc
	v_cmp_class_f32_e32 vcc, v180, v92
	s_nop 1
	v_cndmask_b32_e32 v180, v181, v180, vcc
	v_div_scale_f32 v181, s[0:1], v180, v180, 1.0
	v_rcp_f32_e32 v97, v181
	s_nop 0
	v_fma_f32 v100, -v181, v97, 1.0
	v_fmac_f32_e32 v97, v100, v97
	v_div_scale_f32 v100, vcc, 1.0, v180, 1.0
	v_mul_f32_e32 v101, v100, v97
	v_fma_f32 v104, -v181, v101, v100
	v_fmac_f32_e32 v101, v104, v97
	v_fma_f32 v181, -v181, v101, v100
	v_div_fmas_f32 v181, v181, v97, v101
	v_div_fixup_f32 v100, v181, v180, 1.0
	v_mov_b32_e32 v180, v182
	v_mov_b32_e32 v181, v176
	v_mov_b32_e32 v176, v183
	v_pk_mul_f32 v[180:181], v[100:101], v[180:181] op_sel_hi:[0,1]
	v_pk_mul_f32 v[182:183], v[100:101], v[176:177] op_sel_hi:[0,1]
	v_mov_b32_e32 v176, v102
	v_mov_b32_e32 v177, v178
	v_mov_b32_e32 v178, v103
	v_pk_fma_f32 v[182:183], v[70:71], v[182:183], v[22:23]
	v_pk_fma_f32 v[180:181], v[72:73], v[180:181], v[20:21]
	v_pk_mul_f32 v[176:177], v[100:101], v[176:177] op_sel_hi:[0,1]
	v_pk_mul_f32 v[178:179], v[100:101], v[178:179] op_sel_hi:[0,1]
	s_mov_b64 s[6:7], 0x800
	v_lshl_add_u64 v[104:105], s[6:7], 1, v[68:69]
	v_pk_fma_f32 v[178:179], v[74:75], v[178:179], v[18:19]
	v_pk_fma_f32 v[176:177], v[76:77], v[176:177], v[16:17]
	v_cvt_pk_bf16_f32 v180, v180, v181
	v_cvt_pk_bf16_f32 v181, v182, v183
	v_mov_b32_e32 v97, v61
	v_cvt_pk_bf16_f32 v182, v176, v177
	v_cvt_pk_bf16_f32 v183, v178, v179
	global_store_dwordx4 v[104:105], v[180:183], off
	v_pk_mul_f32 v[176:177], v[96:97], v[100:101] op_sel_hi:[1,0]
	v_pk_mul_f32 v[178:179], v[98:99], v[100:101] op_sel_hi:[1,0]
	v_pk_mul_f32 v[180:181], v[94:95], v[100:101] op_sel_hi:[1,0]
	v_pk_mul_f32 v[182:183], v[108:109], v[100:101] op_sel_hi:[1,0]
	v_pk_fma_f32 v[180:181], v[80:81], v[180:181], v[28:29]
	v_pk_fma_f32 v[182:183], v[78:79], v[182:183], v[30:31]
	v_pk_fma_f32 v[178:179], v[82:83], v[178:179], v[26:27]
	v_pk_fma_f32 v[176:177], v[84:85], v[176:177], v[24:25]
	v_cvt_pk_bf16_f32 v180, v180, v181
	v_cvt_pk_bf16_f32 v181, v182, v183
	s_nop 0
	v_cvt_pk_bf16_f32 v182, v176, v177
	v_cvt_pk_bf16_f32 v183, v178, v179
	global_store_dwordx4 v[104:105], v[180:183], off offset:1024
	s_nop 0
	s_nop 0
	s_nop 0
	s_nop 0
	s_nop 0
	s_nop 0
	s_nop 0
	s_nop 0
	s_waitcnt vmcnt(14)
	v_lshlrev_b32_e32 v96, 16, v190
	v_and_b32_e32 v61, 0xffff0000, v190
	v_lshlrev_b32_e32 v98, 16, v191
	v_and_b32_e32 v99, 0xffff0000, v191
	v_lshlrev_b32_e32 v191, 16, v185
	v_lshlrev_b32_e32 v190, 16, v184
	v_and_b32_e32 v185, 0xffff0000, v185
	v_and_b32_e32 v184, 0xffff0000, v184
	v_lshlrev_b32_e32 v103, 16, v187
	v_lshlrev_b32_e32 v102, 16, v186
	v_and_b32_e32 v187, 0xffff0000, v187
	v_and_b32_e32 v186, 0xffff0000, v186
	v_lshlrev_b32_e32 v94, 16, v188
	v_and_b32_e32 v95, 0xffff0000, v188
	v_pk_mul_f32 v[100:101], v[184:185], v[184:185]
	v_pk_mul_f32 v[104:105], v[186:187], v[186:187]
	v_lshlrev_b32_e32 v108, 16, v189
	v_pk_fma_f32 v[100:101], v[190:191], v[190:191], v[100:101]
	v_pk_fma_f32 v[104:105], v[102:103], v[102:103], v[104:105]
	v_mul_f32_e32 v97, v94, v94
	v_mul_f32_e32 v107, v95, v95
	v_and_b32_e32 v109, 0xffff0000, v189
	v_mul_f32_e32 v188, v108, v108
	v_mov_b32_e32 v106, v96
	v_pk_add_f32 v[100:101], v[100:101], v[100:101] op_sel_hi:[0,1]
	v_pk_add_f32 v[104:105], v[104:105], v[104:105] op_sel_hi:[0,1]
	v_pk_fma_f32 v[188:189], v[108:109], v[108:109], v[188:189] op_sel_hi:[1,1,0]
	v_pk_add_f32 v[106:107], v[96:97], v[106:107]
	v_mul_f32_e32 v188, v61, v61
	v_mul_f32_e32 v100, v98, v98
	v_mul_f32_e32 v104, v99, v99
	v_mul_f32_e32 v110, v96, v96
	v_mov_b32_e32 v111, v107
	v_pk_add_f32 v[188:189], v[110:111], v[188:189]
	v_pk_add_f32 v[100:101], v[100:101], v[104:105]
	v_pk_add_f32 v[188:189], v[188:189], v[100:101]
	v_add_f32_e32 v188, v188, v189
	s_nop 1
	v_add_f32_dpp v188, v188, v188 quad_perm:[1,0,3,2] row_mask:0xf bank_mask:0xf
	s_nop 1
	v_add_f32_dpp v188, v188, v188 quad_perm:[2,3,0,1] row_mask:0xf bank_mask:0xf
	s_nop 1
	v_add_f32_dpp v188, v188, v188 row_half_mirror row_mask:0xf bank_mask:0xf
	s_nop 1
	v_add_f32_dpp v188, v188, v188 row_ror:8 row_mask:0xf bank_mask:0xf
	v_mov_b32_e32 v189, v188
	s_nop 1
	v_permlane16_swap_b32_e32 v189, v188
	v_add_f32_e32 v188, v188, v189
	v_mov_b32_e32 v189, v188
	s_nop 1
	v_permlane32_swap_b32_e32 v189, v188
	v_add_f32_e32 v188, v188, v189
	v_fmamk_f32 v188, v188, 0x3a800000, v49
	v_mul_f32_e32 v189, 0x4f800000, v188
	v_cmp_gt_f32_e32 vcc, s9, v188
	s_nop 1
	v_cndmask_b32_e32 v188, v188, v189, vcc
	v_sqrt_f32_e32 v189, v188
	s_nop 0
	v_add_u32_e32 v97, -1, v189
	v_fma_f32 v100, -v97, v189, v188
	v_cmp_ge_f32_e64 s[0:1], 0, v100
	v_add_u32_e32 v100, 1, v189
	s_nop 0
	v_cndmask_b32_e64 v97, v189, v97, s[0:1]
	v_fma_f32 v189, -v100, v189, v188
	v_cmp_lt_f32_e64 s[0:1], 0, v189
	s_nop 1
	v_cndmask_b32_e64 v189, v97, v100, s[0:1]
	v_mul_f32_e32 v97, 0x37800000, v189
	v_cndmask_b32_e32 v189, v189, v97, vcc
	v_cmp_class_f32_e32 vcc, v188, v92
	s_nop 1
	v_cndmask_b32_e32 v188, v189, v188, vcc
	v_div_scale_f32 v189, s[0:1], v188, v188, 1.0
	v_rcp_f32_e32 v97, v189
	s_nop 0
	v_fma_f32 v100, -v189, v97, 1.0
	v_fmac_f32_e32 v97, v100, v97
	v_div_scale_f32 v100, vcc, 1.0, v188, 1.0
	v_mul_f32_e32 v101, v100, v97
	v_fma_f32 v104, -v189, v101, v100
	v_fmac_f32_e32 v101, v104, v97
	v_fma_f32 v189, -v189, v101, v100
	v_div_fmas_f32 v189, v189, v97, v101
	v_div_fixup_f32 v100, v189, v188, 1.0
	v_mov_b32_e32 v188, v190
	v_mov_b32_e32 v189, v184
	v_mov_b32_e32 v184, v191
	v_pk_mul_f32 v[188:189], v[100:101], v[188:189] op_sel_hi:[0,1]
	v_pk_mul_f32 v[190:191], v[100:101], v[184:185] op_sel_hi:[0,1]
	v_mov_b32_e32 v184, v102
	v_mov_b32_e32 v185, v186
	v_mov_b32_e32 v186, v103
	v_pk_fma_f32 v[190:191], v[70:71], v[190:191], v[22:23]
	v_pk_fma_f32 v[188:189], v[72:73], v[188:189], v[20:21]
	v_pk_mul_f32 v[184:185], v[100:101], v[184:185] op_sel_hi:[0,1]
	v_pk_mul_f32 v[186:187], v[100:101], v[186:187] op_sel_hi:[0,1]
	s_mov_b64 s[6:7], 0xc00
	v_lshl_add_u64 v[104:105], s[6:7], 1, v[68:69]
	v_pk_fma_f32 v[186:187], v[74:75], v[186:187], v[18:19]
	v_pk_fma_f32 v[184:185], v[76:77], v[184:185], v[16:17]
	v_cvt_pk_bf16_f32 v188, v188, v189
	v_cvt_pk_bf16_f32 v189, v190, v191
	v_mov_b32_e32 v97, v61
	v_cvt_pk_bf16_f32 v190, v184, v185
	v_cvt_pk_bf16_f32 v191, v186, v187
	global_store_dwordx4 v[104:105], v[188:191], off
	v_pk_mul_f32 v[184:185], v[96:97], v[100:101] op_sel_hi:[1,0]
	v_pk_mul_f32 v[186:187], v[98:99], v[100:101] op_sel_hi:[1,0]
	v_pk_mul_f32 v[188:189], v[94:95], v[100:101] op_sel_hi:[1,0]
	v_pk_mul_f32 v[190:191], v[108:109], v[100:101] op_sel_hi:[1,0]
	v_pk_fma_f32 v[188:189], v[80:81], v[188:189], v[28:29]
	v_pk_fma_f32 v[190:191], v[78:79], v[190:191], v[30:31]
	v_pk_fma_f32 v[186:187], v[82:83], v[186:187], v[26:27]
	v_pk_fma_f32 v[184:185], v[84:85], v[184:185], v[24:25]
	v_cvt_pk_bf16_f32 v188, v188, v189
	v_cvt_pk_bf16_f32 v189, v190, v191
	s_nop 0
	v_cvt_pk_bf16_f32 v190, v184, v185
	v_cvt_pk_bf16_f32 v191, v186, v187
	global_store_dwordx4 v[104:105], v[188:191], off offset:1024
	s_nop 0
	s_nop 0
	s_nop 0
	s_nop 0
	s_nop 0
	s_nop 0
	s_nop 0
	s_nop 0
	s_waitcnt vmcnt(14)
	v_lshlrev_b32_e32 v96, 16, v198
	v_and_b32_e32 v61, 0xffff0000, v198
	v_lshlrev_b32_e32 v98, 16, v199
	v_and_b32_e32 v99, 0xffff0000, v199
	v_lshlrev_b32_e32 v199, 16, v193
	v_lshlrev_b32_e32 v198, 16, v192
	v_and_b32_e32 v193, 0xffff0000, v193
	v_and_b32_e32 v192, 0xffff0000, v192
	v_lshlrev_b32_e32 v103, 16, v195
	v_lshlrev_b32_e32 v102, 16, v194
	v_and_b32_e32 v195, 0xffff0000, v195
	v_and_b32_e32 v194, 0xffff0000, v194
	v_lshlrev_b32_e32 v94, 16, v196
	v_and_b32_e32 v95, 0xffff0000, v196
	v_pk_mul_f32 v[100:101], v[192:193], v[192:193]
	v_pk_mul_f32 v[104:105], v[194:195], v[194:195]
	v_lshlrev_b32_e32 v108, 16, v197
	v_pk_fma_f32 v[100:101], v[198:199], v[198:199], v[100:101]
	v_pk_fma_f32 v[104:105], v[102:103], v[102:103], v[104:105]
	v_mul_f32_e32 v97, v94, v94
	v_mul_f32_e32 v107, v95, v95
	v_and_b32_e32 v109, 0xffff0000, v197
	v_mul_f32_e32 v196, v108, v108
	v_mov_b32_e32 v106, v96
	v_pk_add_f32 v[100:101], v[100:101], v[100:101] op_sel_hi:[0,1]
	v_pk_add_f32 v[104:105], v[104:105], v[104:105] op_sel_hi:[0,1]
	v_pk_fma_f32 v[196:197], v[108:109], v[108:109], v[196:197] op_sel_hi:[1,1,0]
	v_pk_add_f32 v[106:107], v[96:97], v[106:107]
	v_mul_f32_e32 v196, v61, v61
	v_mul_f32_e32 v100, v98, v98
	v_mul_f32_e32 v104, v99, v99
	v_mul_f32_e32 v110, v96, v96
	v_mov_b32_e32 v111, v107
	v_pk_add_f32 v[196:197], v[110:111], v[196:197]
	v_pk_add_f32 v[100:101], v[100:101], v[104:105]
	v_pk_add_f32 v[196:197], v[196:197], v[100:101]
	v_add_f32_e32 v196, v196, v197
	s_nop 1
	v_add_f32_dpp v196, v196, v196 quad_perm:[1,0,3,2] row_mask:0xf bank_mask:0xf
	s_nop 1
	v_add_f32_dpp v196, v196, v196 quad_perm:[2,3,0,1] row_mask:0xf bank_mask:0xf
	s_nop 1
	v_add_f32_dpp v196, v196, v196 row_half_mirror row_mask:0xf bank_mask:0xf
	s_nop 1
	v_add_f32_dpp v196, v196, v196 row_ror:8 row_mask:0xf bank_mask:0xf
	v_mov_b32_e32 v197, v196
	s_nop 1
	v_permlane16_swap_b32_e32 v197, v196
	v_add_f32_e32 v196, v196, v197
	v_mov_b32_e32 v197, v196
	s_nop 1
	v_permlane32_swap_b32_e32 v197, v196
	v_add_f32_e32 v196, v196, v197
	v_fmamk_f32 v196, v196, 0x3a800000, v49
	v_mul_f32_e32 v197, 0x4f800000, v196
	v_cmp_gt_f32_e32 vcc, s9, v196
	s_nop 1
	v_cndmask_b32_e32 v196, v196, v197, vcc
	v_sqrt_f32_e32 v197, v196
	s_nop 0
	v_add_u32_e32 v97, -1, v197
	v_fma_f32 v100, -v97, v197, v196
	v_cmp_ge_f32_e64 s[0:1], 0, v100
	v_add_u32_e32 v100, 1, v197
	s_nop 0
	v_cndmask_b32_e64 v97, v197, v97, s[0:1]
	v_fma_f32 v197, -v100, v197, v196
	v_cmp_lt_f32_e64 s[0:1], 0, v197
	s_nop 1
	v_cndmask_b32_e64 v197, v97, v100, s[0:1]
	v_mul_f32_e32 v97, 0x37800000, v197
	v_cndmask_b32_e32 v197, v197, v97, vcc
	v_cmp_class_f32_e32 vcc, v196, v92
	s_nop 1
	v_cndmask_b32_e32 v196, v197, v196, vcc
	v_div_scale_f32 v197, s[0:1], v196, v196, 1.0
	v_rcp_f32_e32 v97, v197
	s_nop 0
	v_fma_f32 v100, -v197, v97, 1.0
	v_fmac_f32_e32 v97, v100, v97
	v_div_scale_f32 v100, vcc, 1.0, v196, 1.0
	v_mul_f32_e32 v101, v100, v97
	v_fma_f32 v104, -v197, v101, v100
	v_fmac_f32_e32 v101, v104, v97
	v_fma_f32 v197, -v197, v101, v100
	v_div_fmas_f32 v197, v197, v97, v101
	v_div_fixup_f32 v100, v197, v196, 1.0
	v_mov_b32_e32 v196, v198
	v_mov_b32_e32 v197, v192
	v_mov_b32_e32 v192, v199
	v_pk_mul_f32 v[196:197], v[100:101], v[196:197] op_sel_hi:[0,1]
	v_pk_mul_f32 v[198:199], v[100:101], v[192:193] op_sel_hi:[0,1]
	v_mov_b32_e32 v192, v102
	v_mov_b32_e32 v193, v194
	v_mov_b32_e32 v194, v103
	v_pk_fma_f32 v[198:199], v[70:71], v[198:199], v[22:23]
	v_pk_fma_f32 v[196:197], v[72:73], v[196:197], v[20:21]
	v_pk_mul_f32 v[192:193], v[100:101], v[192:193] op_sel_hi:[0,1]
	v_pk_mul_f32 v[194:195], v[100:101], v[194:195] op_sel_hi:[0,1]
	s_mov_b64 s[6:7], 0x1000
	v_lshl_add_u64 v[104:105], s[6:7], 1, v[68:69]
	v_pk_fma_f32 v[194:195], v[74:75], v[194:195], v[18:19]
	v_pk_fma_f32 v[192:193], v[76:77], v[192:193], v[16:17]
	v_cvt_pk_bf16_f32 v196, v196, v197
	v_cvt_pk_bf16_f32 v197, v198, v199
	v_mov_b32_e32 v97, v61
	v_cvt_pk_bf16_f32 v198, v192, v193
	v_cvt_pk_bf16_f32 v199, v194, v195
	global_store_dwordx4 v[104:105], v[196:199], off
	v_pk_mul_f32 v[192:193], v[96:97], v[100:101] op_sel_hi:[1,0]
	v_pk_mul_f32 v[194:195], v[98:99], v[100:101] op_sel_hi:[1,0]
	v_pk_mul_f32 v[196:197], v[94:95], v[100:101] op_sel_hi:[1,0]
	v_pk_mul_f32 v[198:199], v[108:109], v[100:101] op_sel_hi:[1,0]
	v_pk_fma_f32 v[196:197], v[80:81], v[196:197], v[28:29]
	v_pk_fma_f32 v[198:199], v[78:79], v[198:199], v[30:31]
	v_pk_fma_f32 v[194:195], v[82:83], v[194:195], v[26:27]
	v_pk_fma_f32 v[192:193], v[84:85], v[192:193], v[24:25]
	v_cvt_pk_bf16_f32 v196, v196, v197
	v_cvt_pk_bf16_f32 v197, v198, v199
	s_nop 0
	v_cvt_pk_bf16_f32 v198, v192, v193
	v_cvt_pk_bf16_f32 v199, v194, v195
	global_store_dwordx4 v[104:105], v[196:199], off offset:1024
	s_nop 0
	s_nop 0
	s_nop 0
	s_nop 0
	s_nop 0
	s_nop 0
	s_nop 0
	s_nop 0
	s_waitcnt vmcnt(14)
	v_lshlrev_b32_e32 v96, 16, v206
	v_and_b32_e32 v61, 0xffff0000, v206
	v_lshlrev_b32_e32 v98, 16, v207
	v_and_b32_e32 v99, 0xffff0000, v207
	v_lshlrev_b32_e32 v207, 16, v201
	v_lshlrev_b32_e32 v206, 16, v200
	v_and_b32_e32 v201, 0xffff0000, v201
	v_and_b32_e32 v200, 0xffff0000, v200
	v_lshlrev_b32_e32 v103, 16, v203
	v_lshlrev_b32_e32 v102, 16, v202
	v_and_b32_e32 v203, 0xffff0000, v203
	v_and_b32_e32 v202, 0xffff0000, v202
	v_lshlrev_b32_e32 v94, 16, v204
	v_and_b32_e32 v95, 0xffff0000, v204
	v_pk_mul_f32 v[100:101], v[200:201], v[200:201]
	v_pk_mul_f32 v[104:105], v[202:203], v[202:203]
	v_lshlrev_b32_e32 v108, 16, v205
	v_pk_fma_f32 v[100:101], v[206:207], v[206:207], v[100:101]
	v_pk_fma_f32 v[104:105], v[102:103], v[102:103], v[104:105]
	v_mul_f32_e32 v97, v94, v94
	v_mul_f32_e32 v107, v95, v95
	v_and_b32_e32 v109, 0xffff0000, v205
	v_mul_f32_e32 v204, v108, v108
	v_mov_b32_e32 v106, v96
	v_pk_add_f32 v[100:101], v[100:101], v[100:101] op_sel_hi:[0,1]
	v_pk_add_f32 v[104:105], v[104:105], v[104:105] op_sel_hi:[0,1]
	v_pk_fma_f32 v[204:205], v[108:109], v[108:109], v[204:205] op_sel_hi:[1,1,0]
	v_pk_add_f32 v[106:107], v[96:97], v[106:107]
	v_mul_f32_e32 v204, v61, v61
	v_mul_f32_e32 v100, v98, v98
	v_mul_f32_e32 v104, v99, v99
	v_mul_f32_e32 v110, v96, v96
	v_mov_b32_e32 v111, v107
	v_pk_add_f32 v[204:205], v[110:111], v[204:205]
	v_pk_add_f32 v[100:101], v[100:101], v[104:105]
	v_pk_add_f32 v[204:205], v[204:205], v[100:101]
	v_add_f32_e32 v204, v204, v205
	s_nop 1
	v_add_f32_dpp v204, v204, v204 quad_perm:[1,0,3,2] row_mask:0xf bank_mask:0xf
	s_nop 1
	v_add_f32_dpp v204, v204, v204 quad_perm:[2,3,0,1] row_mask:0xf bank_mask:0xf
	s_nop 1
	v_add_f32_dpp v204, v204, v204 row_half_mirror row_mask:0xf bank_mask:0xf
	s_nop 1
	v_add_f32_dpp v204, v204, v204 row_ror:8 row_mask:0xf bank_mask:0xf
	v_mov_b32_e32 v205, v204
	s_nop 1
	v_permlane16_swap_b32_e32 v205, v204
	v_add_f32_e32 v204, v204, v205
	v_mov_b32_e32 v205, v204
	s_nop 1
	v_permlane32_swap_b32_e32 v205, v204
	v_add_f32_e32 v204, v204, v205
	v_fmamk_f32 v204, v204, 0x3a800000, v49
	v_mul_f32_e32 v205, 0x4f800000, v204
	v_cmp_gt_f32_e32 vcc, s9, v204
	s_nop 1
	v_cndmask_b32_e32 v204, v204, v205, vcc
	v_sqrt_f32_e32 v205, v204
	s_nop 0
	v_add_u32_e32 v97, -1, v205
	v_fma_f32 v100, -v97, v205, v204
	v_cmp_ge_f32_e64 s[0:1], 0, v100
	v_add_u32_e32 v100, 1, v205
	s_nop 0
	v_cndmask_b32_e64 v97, v205, v97, s[0:1]
	v_fma_f32 v205, -v100, v205, v204
	v_cmp_lt_f32_e64 s[0:1], 0, v205
	s_nop 1
	v_cndmask_b32_e64 v205, v97, v100, s[0:1]
	v_mul_f32_e32 v97, 0x37800000, v205
	v_cndmask_b32_e32 v205, v205, v97, vcc
	v_cmp_class_f32_e32 vcc, v204, v92
	s_nop 1
	v_cndmask_b32_e32 v204, v205, v204, vcc
	v_div_scale_f32 v205, s[0:1], v204, v204, 1.0
	v_rcp_f32_e32 v97, v205
	s_nop 0
	v_fma_f32 v100, -v205, v97, 1.0
	v_fmac_f32_e32 v97, v100, v97
	v_div_scale_f32 v100, vcc, 1.0, v204, 1.0
	v_mul_f32_e32 v101, v100, v97
	v_fma_f32 v104, -v205, v101, v100
	v_fmac_f32_e32 v101, v104, v97
	v_fma_f32 v205, -v205, v101, v100
	v_div_fmas_f32 v205, v205, v97, v101
	v_div_fixup_f32 v100, v205, v204, 1.0
	v_mov_b32_e32 v204, v206
	v_mov_b32_e32 v205, v200
	v_mov_b32_e32 v200, v207
	v_pk_mul_f32 v[204:205], v[100:101], v[204:205] op_sel_hi:[0,1]
	v_pk_mul_f32 v[206:207], v[100:101], v[200:201] op_sel_hi:[0,1]
	v_mov_b32_e32 v200, v102
	v_mov_b32_e32 v201, v202
	v_mov_b32_e32 v202, v103
	v_pk_fma_f32 v[206:207], v[70:71], v[206:207], v[22:23]
	v_pk_fma_f32 v[204:205], v[72:73], v[204:205], v[20:21]
	v_pk_mul_f32 v[200:201], v[100:101], v[200:201] op_sel_hi:[0,1]
	v_pk_mul_f32 v[202:203], v[100:101], v[202:203] op_sel_hi:[0,1]
	s_mov_b64 s[6:7], 0x1400
	v_lshl_add_u64 v[104:105], s[6:7], 1, v[68:69]
	v_pk_fma_f32 v[202:203], v[74:75], v[202:203], v[18:19]
	v_pk_fma_f32 v[200:201], v[76:77], v[200:201], v[16:17]
	v_cvt_pk_bf16_f32 v204, v204, v205
	v_cvt_pk_bf16_f32 v205, v206, v207
	v_mov_b32_e32 v97, v61
	v_cvt_pk_bf16_f32 v206, v200, v201
	v_cvt_pk_bf16_f32 v207, v202, v203
	global_store_dwordx4 v[104:105], v[204:207], off
	v_pk_mul_f32 v[200:201], v[96:97], v[100:101] op_sel_hi:[1,0]
	v_pk_mul_f32 v[202:203], v[98:99], v[100:101] op_sel_hi:[1,0]
	v_pk_mul_f32 v[204:205], v[94:95], v[100:101] op_sel_hi:[1,0]
	v_pk_mul_f32 v[206:207], v[108:109], v[100:101] op_sel_hi:[1,0]
	v_pk_fma_f32 v[204:205], v[80:81], v[204:205], v[28:29]
	v_pk_fma_f32 v[206:207], v[78:79], v[206:207], v[30:31]
	v_pk_fma_f32 v[202:203], v[82:83], v[202:203], v[26:27]
	v_pk_fma_f32 v[200:201], v[84:85], v[200:201], v[24:25]
	v_cvt_pk_bf16_f32 v204, v204, v205
	v_cvt_pk_bf16_f32 v205, v206, v207
	s_nop 0
	v_cvt_pk_bf16_f32 v206, v200, v201
	v_cvt_pk_bf16_f32 v207, v202, v203
	global_store_dwordx4 v[104:105], v[204:207], off offset:1024
	s_nop 0
	s_nop 0
	s_nop 0
	s_nop 0
	s_nop 0
	s_nop 0
	s_nop 0
	s_nop 0
	s_waitcnt vmcnt(14)
	v_lshlrev_b32_e32 v96, 16, v214
	v_and_b32_e32 v61, 0xffff0000, v214
	v_lshlrev_b32_e32 v98, 16, v215
	v_and_b32_e32 v99, 0xffff0000, v215
	v_lshlrev_b32_e32 v215, 16, v209
	v_lshlrev_b32_e32 v214, 16, v208
	v_and_b32_e32 v209, 0xffff0000, v209
	v_and_b32_e32 v208, 0xffff0000, v208
	v_lshlrev_b32_e32 v103, 16, v211
	v_lshlrev_b32_e32 v102, 16, v210
	v_and_b32_e32 v211, 0xffff0000, v211
	v_and_b32_e32 v210, 0xffff0000, v210
	v_lshlrev_b32_e32 v94, 16, v212
	v_and_b32_e32 v95, 0xffff0000, v212
	v_pk_mul_f32 v[100:101], v[208:209], v[208:209]
	v_pk_mul_f32 v[104:105], v[210:211], v[210:211]
	v_lshlrev_b32_e32 v108, 16, v213
	v_pk_fma_f32 v[100:101], v[214:215], v[214:215], v[100:101]
	v_pk_fma_f32 v[104:105], v[102:103], v[102:103], v[104:105]
	v_mul_f32_e32 v97, v94, v94
	v_mul_f32_e32 v107, v95, v95
	v_and_b32_e32 v109, 0xffff0000, v213
	v_mul_f32_e32 v212, v108, v108
	v_mov_b32_e32 v106, v96
	v_pk_add_f32 v[100:101], v[100:101], v[100:101] op_sel_hi:[0,1]
	v_pk_add_f32 v[104:105], v[104:105], v[104:105] op_sel_hi:[0,1]
	v_pk_fma_f32 v[212:213], v[108:109], v[108:109], v[212:213] op_sel_hi:[1,1,0]
	v_pk_add_f32 v[106:107], v[96:97], v[106:107]
	v_mul_f32_e32 v212, v61, v61
	v_mul_f32_e32 v100, v98, v98
	v_mul_f32_e32 v104, v99, v99
	v_mul_f32_e32 v110, v96, v96
	v_mov_b32_e32 v111, v107
	v_pk_add_f32 v[212:213], v[110:111], v[212:213]
	v_pk_add_f32 v[100:101], v[100:101], v[104:105]
	v_pk_add_f32 v[212:213], v[212:213], v[100:101]
	v_add_f32_e32 v212, v212, v213
	s_nop 1
	v_add_f32_dpp v212, v212, v212 quad_perm:[1,0,3,2] row_mask:0xf bank_mask:0xf
	s_nop 1
	v_add_f32_dpp v212, v212, v212 quad_perm:[2,3,0,1] row_mask:0xf bank_mask:0xf
	s_nop 1
	v_add_f32_dpp v212, v212, v212 row_half_mirror row_mask:0xf bank_mask:0xf
	s_nop 1
	v_add_f32_dpp v212, v212, v212 row_ror:8 row_mask:0xf bank_mask:0xf
	v_mov_b32_e32 v213, v212
	s_nop 1
	v_permlane16_swap_b32_e32 v213, v212
	v_add_f32_e32 v212, v212, v213
	v_mov_b32_e32 v213, v212
	s_nop 1
	v_permlane32_swap_b32_e32 v213, v212
	v_add_f32_e32 v212, v212, v213
	v_fmamk_f32 v212, v212, 0x3a800000, v49
	v_mul_f32_e32 v213, 0x4f800000, v212
	v_cmp_gt_f32_e32 vcc, s9, v212
	s_nop 1
	v_cndmask_b32_e32 v212, v212, v213, vcc
	v_sqrt_f32_e32 v213, v212
	s_nop 0
	v_add_u32_e32 v97, -1, v213
	v_fma_f32 v100, -v97, v213, v212
	v_cmp_ge_f32_e64 s[0:1], 0, v100
	v_add_u32_e32 v100, 1, v213
	s_nop 0
	v_cndmask_b32_e64 v97, v213, v97, s[0:1]
	v_fma_f32 v213, -v100, v213, v212
	v_cmp_lt_f32_e64 s[0:1], 0, v213
	s_nop 1
	v_cndmask_b32_e64 v213, v97, v100, s[0:1]
	v_mul_f32_e32 v97, 0x37800000, v213
	v_cndmask_b32_e32 v213, v213, v97, vcc
	v_cmp_class_f32_e32 vcc, v212, v92
	s_nop 1
	v_cndmask_b32_e32 v212, v213, v212, vcc
	v_div_scale_f32 v213, s[0:1], v212, v212, 1.0
	v_rcp_f32_e32 v97, v213
	s_nop 0
	v_fma_f32 v100, -v213, v97, 1.0
	v_fmac_f32_e32 v97, v100, v97
	v_div_scale_f32 v100, vcc, 1.0, v212, 1.0
	v_mul_f32_e32 v101, v100, v97
	v_fma_f32 v104, -v213, v101, v100
	v_fmac_f32_e32 v101, v104, v97
	v_fma_f32 v213, -v213, v101, v100
	v_div_fmas_f32 v213, v213, v97, v101
	v_div_fixup_f32 v100, v213, v212, 1.0
	v_mov_b32_e32 v212, v214
	v_mov_b32_e32 v213, v208
	v_mov_b32_e32 v208, v215
	v_pk_mul_f32 v[212:213], v[100:101], v[212:213] op_sel_hi:[0,1]
	v_pk_mul_f32 v[214:215], v[100:101], v[208:209] op_sel_hi:[0,1]
	v_mov_b32_e32 v208, v102
	v_mov_b32_e32 v209, v210
	v_mov_b32_e32 v210, v103
	v_pk_fma_f32 v[214:215], v[70:71], v[214:215], v[22:23]
	v_pk_fma_f32 v[212:213], v[72:73], v[212:213], v[20:21]
	v_pk_mul_f32 v[208:209], v[100:101], v[208:209] op_sel_hi:[0,1]
	v_pk_mul_f32 v[210:211], v[100:101], v[210:211] op_sel_hi:[0,1]
	s_mov_b64 s[6:7], 0x1800
	v_lshl_add_u64 v[104:105], s[6:7], 1, v[68:69]
	v_pk_fma_f32 v[210:211], v[74:75], v[210:211], v[18:19]
	v_pk_fma_f32 v[208:209], v[76:77], v[208:209], v[16:17]
	v_cvt_pk_bf16_f32 v212, v212, v213
	v_cvt_pk_bf16_f32 v213, v214, v215
	v_mov_b32_e32 v97, v61
	v_cvt_pk_bf16_f32 v214, v208, v209
	v_cvt_pk_bf16_f32 v215, v210, v211
	global_store_dwordx4 v[104:105], v[212:215], off
	v_pk_mul_f32 v[208:209], v[96:97], v[100:101] op_sel_hi:[1,0]
	v_pk_mul_f32 v[210:211], v[98:99], v[100:101] op_sel_hi:[1,0]
	v_pk_mul_f32 v[212:213], v[94:95], v[100:101] op_sel_hi:[1,0]
	v_pk_mul_f32 v[214:215], v[108:109], v[100:101] op_sel_hi:[1,0]
	v_pk_fma_f32 v[212:213], v[80:81], v[212:213], v[28:29]
	v_pk_fma_f32 v[214:215], v[78:79], v[214:215], v[30:31]
	v_pk_fma_f32 v[210:211], v[82:83], v[210:211], v[26:27]
	v_pk_fma_f32 v[208:209], v[84:85], v[208:209], v[24:25]
	v_cvt_pk_bf16_f32 v212, v212, v213
	v_cvt_pk_bf16_f32 v213, v214, v215
	s_nop 0
	v_cvt_pk_bf16_f32 v214, v208, v209
	v_cvt_pk_bf16_f32 v215, v210, v211
	global_store_dwordx4 v[104:105], v[212:215], off offset:1024
	s_nop 0
	s_nop 0
	s_nop 0
	s_nop 0
	s_nop 0
	s_nop 0
	s_nop 0
	s_nop 0
	s_waitcnt vmcnt(14)
	v_lshlrev_b32_e32 v96, 16, v222
	v_and_b32_e32 v61, 0xffff0000, v222
	v_lshlrev_b32_e32 v98, 16, v223
	v_and_b32_e32 v99, 0xffff0000, v223
	v_lshlrev_b32_e32 v223, 16, v217
	v_lshlrev_b32_e32 v222, 16, v216
	v_and_b32_e32 v217, 0xffff0000, v217
	v_and_b32_e32 v216, 0xffff0000, v216
	v_lshlrev_b32_e32 v103, 16, v219
	v_lshlrev_b32_e32 v102, 16, v218
	v_and_b32_e32 v219, 0xffff0000, v219
	v_and_b32_e32 v218, 0xffff0000, v218
	v_lshlrev_b32_e32 v94, 16, v220
	v_and_b32_e32 v95, 0xffff0000, v220
	v_pk_mul_f32 v[100:101], v[216:217], v[216:217]
	v_pk_mul_f32 v[104:105], v[218:219], v[218:219]
	v_lshlrev_b32_e32 v108, 16, v221
	v_pk_fma_f32 v[100:101], v[222:223], v[222:223], v[100:101]
	v_pk_fma_f32 v[104:105], v[102:103], v[102:103], v[104:105]
	v_mul_f32_e32 v97, v94, v94
	v_mul_f32_e32 v107, v95, v95
	v_and_b32_e32 v109, 0xffff0000, v221
	v_mul_f32_e32 v220, v108, v108
	v_mov_b32_e32 v106, v96
	v_pk_add_f32 v[100:101], v[100:101], v[100:101] op_sel_hi:[0,1]
	v_pk_add_f32 v[104:105], v[104:105], v[104:105] op_sel_hi:[0,1]
	v_pk_fma_f32 v[220:221], v[108:109], v[108:109], v[220:221] op_sel_hi:[1,1,0]
	v_pk_add_f32 v[106:107], v[96:97], v[106:107]
	v_mul_f32_e32 v220, v61, v61
	v_mul_f32_e32 v100, v98, v98
	v_mul_f32_e32 v104, v99, v99
	v_mul_f32_e32 v110, v96, v96
	v_mov_b32_e32 v111, v107
	v_pk_add_f32 v[220:221], v[110:111], v[220:221]
	v_pk_add_f32 v[100:101], v[100:101], v[104:105]
	v_pk_add_f32 v[220:221], v[220:221], v[100:101]
	v_add_f32_e32 v220, v220, v221
	s_nop 1
	v_add_f32_dpp v220, v220, v220 quad_perm:[1,0,3,2] row_mask:0xf bank_mask:0xf
	s_nop 1
	v_add_f32_dpp v220, v220, v220 quad_perm:[2,3,0,1] row_mask:0xf bank_mask:0xf
	s_nop 1
	v_add_f32_dpp v220, v220, v220 row_half_mirror row_mask:0xf bank_mask:0xf
	s_nop 1
	v_add_f32_dpp v220, v220, v220 row_ror:8 row_mask:0xf bank_mask:0xf
	v_mov_b32_e32 v221, v220
	s_nop 1
	v_permlane16_swap_b32_e32 v221, v220
	v_add_f32_e32 v220, v220, v221
	v_mov_b32_e32 v221, v220
	s_nop 1
	v_permlane32_swap_b32_e32 v221, v220
	v_add_f32_e32 v220, v220, v221
	v_fmamk_f32 v220, v220, 0x3a800000, v49
	v_mul_f32_e32 v221, 0x4f800000, v220
	v_cmp_gt_f32_e32 vcc, s9, v220
	s_nop 1
	v_cndmask_b32_e32 v220, v220, v221, vcc
	v_sqrt_f32_e32 v221, v220
	s_nop 0
	v_add_u32_e32 v97, -1, v221
	v_fma_f32 v100, -v97, v221, v220
	v_cmp_ge_f32_e64 s[0:1], 0, v100
	v_add_u32_e32 v100, 1, v221
	s_nop 0
	v_cndmask_b32_e64 v97, v221, v97, s[0:1]
	v_fma_f32 v221, -v100, v221, v220
	v_cmp_lt_f32_e64 s[0:1], 0, v221
	s_nop 1
	v_cndmask_b32_e64 v221, v97, v100, s[0:1]
	v_mul_f32_e32 v97, 0x37800000, v221
	v_cndmask_b32_e32 v221, v221, v97, vcc
	v_cmp_class_f32_e32 vcc, v220, v92
	s_nop 1
	v_cndmask_b32_e32 v220, v221, v220, vcc
	v_div_scale_f32 v221, s[0:1], v220, v220, 1.0
	v_rcp_f32_e32 v97, v221
	s_nop 0
	v_fma_f32 v100, -v221, v97, 1.0
	v_fmac_f32_e32 v97, v100, v97
	v_div_scale_f32 v100, vcc, 1.0, v220, 1.0
	v_mul_f32_e32 v101, v100, v97
	v_fma_f32 v104, -v221, v101, v100
	v_fmac_f32_e32 v101, v104, v97
	v_fma_f32 v221, -v221, v101, v100
	v_div_fmas_f32 v221, v221, v97, v101
	v_div_fixup_f32 v100, v221, v220, 1.0
	v_mov_b32_e32 v220, v222
	v_mov_b32_e32 v221, v216
	v_mov_b32_e32 v216, v223
	v_pk_mul_f32 v[220:221], v[100:101], v[220:221] op_sel_hi:[0,1]
	v_pk_mul_f32 v[222:223], v[100:101], v[216:217] op_sel_hi:[0,1]
	v_mov_b32_e32 v216, v102
	v_mov_b32_e32 v217, v218
	v_mov_b32_e32 v218, v103
	v_pk_fma_f32 v[222:223], v[70:71], v[222:223], v[22:23]
	v_pk_fma_f32 v[220:221], v[72:73], v[220:221], v[20:21]
	v_pk_mul_f32 v[216:217], v[100:101], v[216:217] op_sel_hi:[0,1]
	v_pk_mul_f32 v[218:219], v[100:101], v[218:219] op_sel_hi:[0,1]
	s_mov_b64 s[6:7], 0x1c00
	v_lshl_add_u64 v[104:105], s[6:7], 1, v[68:69]
	v_pk_fma_f32 v[218:219], v[74:75], v[218:219], v[18:19]
	v_pk_fma_f32 v[216:217], v[76:77], v[216:217], v[16:17]
	v_cvt_pk_bf16_f32 v220, v220, v221
	v_cvt_pk_bf16_f32 v221, v222, v223
	v_mov_b32_e32 v97, v61
	v_cvt_pk_bf16_f32 v222, v216, v217
	v_cvt_pk_bf16_f32 v223, v218, v219
	global_store_dwordx4 v[104:105], v[220:223], off
	v_pk_mul_f32 v[216:217], v[96:97], v[100:101] op_sel_hi:[1,0]
	v_pk_mul_f32 v[218:219], v[98:99], v[100:101] op_sel_hi:[1,0]
	v_pk_mul_f32 v[220:221], v[94:95], v[100:101] op_sel_hi:[1,0]
	v_pk_mul_f32 v[222:223], v[108:109], v[100:101] op_sel_hi:[1,0]
	v_pk_fma_f32 v[220:221], v[80:81], v[220:221], v[28:29]
	v_pk_fma_f32 v[222:223], v[78:79], v[222:223], v[30:31]
	v_pk_fma_f32 v[218:219], v[82:83], v[218:219], v[26:27]
	v_pk_fma_f32 v[216:217], v[84:85], v[216:217], v[24:25]
	v_cvt_pk_bf16_f32 v220, v220, v221
	v_cvt_pk_bf16_f32 v221, v222, v223
	s_nop 0
	v_cvt_pk_bf16_f32 v222, v216, v217
	v_cvt_pk_bf16_f32 v223, v218, v219
	global_store_dwordx4 v[104:105], v[220:223], off offset:1024
	s_nop 0
	s_nop 0
	s_nop 0
	s_nop 0
	s_nop 0
	s_nop 0
	s_nop 0
	s_nop 0
	s_branch .LBB0_1144

.LBB0_1390:
	v_ashrrev_i32_e32 v59, 31, v58
	v_lshlrev_b64 v[32:33], 14, v[58:59]
	v_lshl_add_u64 v[32:33], s[22:23], 0, v[32:33]
	v_lshl_add_u64 v[32:33], v[32:33], 0, v[52:53]
	global_load_dwordx4 v[44:47], v[32:33], off
	global_load_dwordx4 v[40:43], v[32:33], off offset:1024
	v_lshlrev_b64 v[32:33], 15, v[58:59]
	v_lshl_add_u64 v[60:61], v[54:55], 0, v[32:33]
	s_mov_b64 s[14:15], 0xc500800
	v_lshl_add_u64 v[226:227], v[56:57], 0, s[14:15]
	global_load_dwordx4 v[32:35], v[226:227], off
	global_load_dwordx4 v[36:39], v[226:227], off offset:1024
	s_mov_b64 s[14:15], 0xc501000
	v_lshl_add_u64 v[224:225], v[56:57], 0, s[14:15]
	global_load_dwordx4 v[176:179], v[224:225], off
	global_load_dwordx4 v[180:183], v[224:225], off offset:1024
	s_mov_b64 s[14:15], 0xc501800
	v_lshl_add_u64 v[226:227], v[56:57], 0, s[14:15]
	global_load_dwordx4 v[184:187], v[226:227], off
	global_load_dwordx4 v[188:191], v[226:227], off offset:1024
	s_mov_b64 s[14:15], 0xc502000
	v_lshl_add_u64 v[224:225], v[56:57], 0, s[14:15]
	global_load_dwordx4 v[192:195], v[224:225], off
	global_load_dwordx4 v[196:199], v[224:225], off offset:1024
	s_mov_b64 s[14:15], 0xc502800
	v_lshl_add_u64 v[226:227], v[56:57], 0, s[14:15]
	global_load_dwordx4 v[200:203], v[226:227], off
	global_load_dwordx4 v[204:207], v[226:227], off offset:1024
	s_mov_b64 s[14:15], 0xc503000
	v_lshl_add_u64 v[224:225], v[56:57], 0, s[14:15]
	global_load_dwordx4 v[208:211], v[224:225], off
	global_load_dwordx4 v[212:215], v[224:225], off offset:1024
	s_mov_b64 s[14:15], 0xc503800
	v_lshl_add_u64 v[226:227], v[56:57], 0, s[14:15]
	global_load_dwordx4 v[216:219], v[226:227], off
	global_load_dwordx4 v[220:223], v[226:227], off offset:1024
	s_waitcnt vmcnt(14)
	v_lshlrev_b32_e32 v72, 16, v42
	v_and_b32_e32 v59, 0xffff0000, v42
	v_lshlrev_b32_e32 v74, 16, v43
	v_and_b32_e32 v75, 0xffff0000, v43
	v_lshlrev_b32_e32 v43, 16, v45
	v_lshlrev_b32_e32 v42, 16, v44
	v_and_b32_e32 v45, 0xffff0000, v45
	v_and_b32_e32 v44, 0xffff0000, v44
	v_lshlrev_b32_e32 v79, 16, v47
	v_lshlrev_b32_e32 v78, 16, v46
	v_and_b32_e32 v47, 0xffff0000, v47
	v_and_b32_e32 v46, 0xffff0000, v46
	v_lshlrev_b32_e32 v70, 16, v40
	v_and_b32_e32 v71, 0xffff0000, v40
	v_pk_mul_f32 v[76:77], v[44:45], v[44:45]
	v_pk_mul_f32 v[80:81], v[46:47], v[46:47]
	v_lshlrev_b32_e32 v84, 16, v41
	v_pk_fma_f32 v[76:77], v[42:43], v[42:43], v[76:77]
	v_pk_fma_f32 v[80:81], v[78:79], v[78:79], v[80:81]
	v_mul_f32_e32 v73, v70, v70
	v_mul_f32_e32 v83, v71, v71
	v_and_b32_e32 v85, 0xffff0000, v41
	v_mul_f32_e32 v40, v84, v84
	v_mov_b32_e32 v82, v72
	v_pk_add_f32 v[76:77], v[76:77], v[76:77] op_sel_hi:[0,1]
	v_pk_add_f32 v[80:81], v[80:81], v[80:81] op_sel_hi:[0,1]
	v_pk_fma_f32 v[40:41], v[84:85], v[84:85], v[40:41] op_sel_hi:[1,1,0]
	v_pk_add_f32 v[82:83], v[72:73], v[82:83]
	v_mul_f32_e32 v40, v59, v59
	v_mul_f32_e32 v76, v74, v74
	v_mul_f32_e32 v80, v75, v75
	v_mul_f32_e32 v86, v72, v72
	v_mov_b32_e32 v87, v83
	v_pk_add_f32 v[40:41], v[86:87], v[40:41]
	v_pk_add_f32 v[76:77], v[76:77], v[80:81]
	v_pk_add_f32 v[40:41], v[40:41], v[76:77]
	v_add_f32_e32 v40, v40, v41
	s_nop 1
	v_add_f32_dpp v40, v40, v40 quad_perm:[1,0,3,2] row_mask:0xf bank_mask:0xf
	s_nop 1
	v_add_f32_dpp v40, v40, v40 quad_perm:[2,3,0,1] row_mask:0xf bank_mask:0xf
	s_nop 1
	v_add_f32_dpp v40, v40, v40 row_half_mirror row_mask:0xf bank_mask:0xf
	s_nop 1
	v_add_f32_dpp v40, v40, v40 row_ror:8 row_mask:0xf bank_mask:0xf
	v_mov_b32_e32 v41, v40
	s_nop 1
	v_permlane16_swap_b32_e32 v41, v40
	v_add_f32_e32 v40, v40, v41
	v_mov_b32_e32 v41, v40
	s_nop 1
	v_permlane32_swap_b32_e32 v41, v40
	v_add_f32_e32 v40, v40, v41
	v_fmamk_f32 v40, v40, 0x3a800000, v68
	v_mul_f32_e32 v41, 0x4f800000, v40
	v_cmp_gt_f32_e32 vcc, s3, v40
	s_nop 1
	v_cndmask_b32_e32 v40, v40, v41, vcc
	v_sqrt_f32_e32 v41, v40
	s_nop 0
	v_add_u32_e32 v73, -1, v41
	v_fma_f32 v76, -v73, v41, v40
	v_cmp_ge_f32_e64 s[0:1], 0, v76
	v_add_u32_e32 v76, 1, v41
	s_nop 0
	v_cndmask_b32_e64 v73, v41, v73, s[0:1]
	v_fma_f32 v41, -v76, v41, v40
	v_cmp_lt_f32_e64 s[0:1], 0, v41
	s_nop 1
	v_cndmask_b32_e64 v41, v73, v76, s[0:1]
	v_mul_f32_e32 v73, 0x37800000, v41
	v_cndmask_b32_e32 v41, v41, v73, vcc
	v_cmp_class_f32_e32 vcc, v40, v69
	s_nop 1
	v_cndmask_b32_e32 v40, v41, v40, vcc
	v_div_scale_f32 v41, s[0:1], v40, v40, 1.0
	v_rcp_f32_e32 v73, v41
	s_nop 0
	v_fma_f32 v76, -v41, v73, 1.0
	v_fmac_f32_e32 v73, v76, v73
	v_div_scale_f32 v76, vcc, 1.0, v40, 1.0
	v_mul_f32_e32 v77, v76, v73
	v_fma_f32 v80, -v41, v77, v76
	v_fmac_f32_e32 v77, v80, v73
	v_fma_f32 v41, -v41, v77, v76
	v_div_fmas_f32 v41, v41, v73, v77
	v_div_fixup_f32 v76, v41, v40, 1.0
	v_mov_b32_e32 v40, v42
	v_mov_b32_e32 v41, v44
	v_mov_b32_e32 v44, v43
	v_pk_mul_f32 v[40:41], v[76:77], v[40:41] op_sel_hi:[0,1]
	v_pk_mul_f32 v[42:43], v[76:77], v[44:45] op_sel_hi:[0,1]
	s_mov_b64 s[14:15], 0x0
	v_lshl_add_u64 v[80:81], s[14:15], 2, v[60:61]
	v_pk_mul_f32 v[42:43], v[22:23], v[42:43]
	v_pk_mul_f32 v[40:41], v[20:21], v[40:41]
	global_store_dwordx4 v[80:81], v[40:43], off
	v_mov_b32_e32 v73, v59
	s_nop 0
	v_mov_b32_e32 v40, v78
	v_mov_b32_e32 v41, v46
	v_mov_b32_e32 v46, v79
	v_pk_mul_f32 v[40:41], v[76:77], v[40:41] op_sel_hi:[0,1]
	v_pk_mul_f32 v[42:43], v[76:77], v[46:47] op_sel_hi:[0,1]
	v_pk_mul_f32 v[42:43], v[18:19], v[42:43]
	v_pk_mul_f32 v[40:41], v[16:17], v[40:41]
	global_store_dwordx4 v[80:81], v[40:43], off offset:16
	s_nop 0
	s_nop 0
	v_pk_mul_f32 v[40:41], v[70:71], v[76:77] op_sel_hi:[1,0]
	v_pk_mul_f32 v[42:43], v[84:85], v[76:77] op_sel_hi:[1,0]
	v_pk_mul_f32 v[40:41], v[28:29], v[40:41]
	v_pk_mul_f32 v[42:43], v[30:31], v[42:43]
	global_store_dwordx4 v[80:81], v[40:43], off offset:2048
	s_nop 0
	s_nop 0
	v_pk_mul_f32 v[40:41], v[72:73], v[76:77] op_sel_hi:[1,0]
	v_pk_mul_f32 v[42:43], v[74:75], v[76:77] op_sel_hi:[1,0]
	v_pk_mul_f32 v[40:41], v[24:25], v[40:41]
	v_pk_mul_f32 v[42:43], v[26:27], v[42:43]
	global_store_dwordx4 v[80:81], v[40:43], off offset:2064
	s_nop 1
	s_nop 0
	s_nop 0
	s_nop 0
	s_nop 0
	s_waitcnt vmcnt(16)
	v_lshlrev_b32_e32 v72, 16, v38
	v_and_b32_e32 v59, 0xffff0000, v38
	v_lshlrev_b32_e32 v74, 16, v39
	v_and_b32_e32 v75, 0xffff0000, v39
	v_lshlrev_b32_e32 v39, 16, v33
	v_lshlrev_b32_e32 v38, 16, v32
	v_and_b32_e32 v33, 0xffff0000, v33
	v_and_b32_e32 v32, 0xffff0000, v32
	v_lshlrev_b32_e32 v79, 16, v35
	v_lshlrev_b32_e32 v78, 16, v34
	v_and_b32_e32 v35, 0xffff0000, v35
	v_and_b32_e32 v34, 0xffff0000, v34
	v_lshlrev_b32_e32 v70, 16, v36
	v_and_b32_e32 v71, 0xffff0000, v36
	v_pk_mul_f32 v[76:77], v[32:33], v[32:33]
	v_pk_mul_f32 v[80:81], v[34:35], v[34:35]
	v_lshlrev_b32_e32 v84, 16, v37
	v_pk_fma_f32 v[76:77], v[38:39], v[38:39], v[76:77]
	v_pk_fma_f32 v[80:81], v[78:79], v[78:79], v[80:81]
	v_mul_f32_e32 v73, v70, v70
	v_mul_f32_e32 v83, v71, v71
	v_and_b32_e32 v85, 0xffff0000, v37
	v_mul_f32_e32 v36, v84, v84
	v_mov_b32_e32 v82, v72
	v_pk_add_f32 v[76:77], v[76:77], v[76:77] op_sel_hi:[0,1]
	v_pk_add_f32 v[80:81], v[80:81], v[80:81] op_sel_hi:[0,1]
	v_pk_fma_f32 v[36:37], v[84:85], v[84:85], v[36:37] op_sel_hi:[1,1,0]
	v_pk_add_f32 v[82:83], v[72:73], v[82:83]
	v_mul_f32_e32 v36, v59, v59
	v_mul_f32_e32 v76, v74, v74
	v_mul_f32_e32 v80, v75, v75
	v_mul_f32_e32 v86, v72, v72
	v_mov_b32_e32 v87, v83
	v_pk_add_f32 v[36:37], v[86:87], v[36:37]
	v_pk_add_f32 v[76:77], v[76:77], v[80:81]
	v_pk_add_f32 v[36:37], v[36:37], v[76:77]
	v_add_f32_e32 v36, v36, v37
	s_nop 1
	v_add_f32_dpp v36, v36, v36 quad_perm:[1,0,3,2] row_mask:0xf bank_mask:0xf
	s_nop 1
	v_add_f32_dpp v36, v36, v36 quad_perm:[2,3,0,1] row_mask:0xf bank_mask:0xf
	s_nop 1
	v_add_f32_dpp v36, v36, v36 row_half_mirror row_mask:0xf bank_mask:0xf
	s_nop 1
	v_add_f32_dpp v36, v36, v36 row_ror:8 row_mask:0xf bank_mask:0xf
	v_mov_b32_e32 v37, v36
	s_nop 1
	v_permlane16_swap_b32_e32 v37, v36
	v_add_f32_e32 v36, v36, v37
	v_mov_b32_e32 v37, v36
	s_nop 1
	v_permlane32_swap_b32_e32 v37, v36
	v_add_f32_e32 v36, v36, v37
	v_fmamk_f32 v36, v36, 0x3a800000, v68
	v_mul_f32_e32 v37, 0x4f800000, v36
	v_cmp_gt_f32_e32 vcc, s3, v36
	s_nop 1
	v_cndmask_b32_e32 v36, v36, v37, vcc
	v_sqrt_f32_e32 v37, v36
	s_nop 0
	v_add_u32_e32 v73, -1, v37
	v_fma_f32 v76, -v73, v37, v36
	v_cmp_ge_f32_e64 s[0:1], 0, v76
	v_add_u32_e32 v76, 1, v37
	s_nop 0
	v_cndmask_b32_e64 v73, v37, v73, s[0:1]
	v_fma_f32 v37, -v76, v37, v36
	v_cmp_lt_f32_e64 s[0:1], 0, v37
	s_nop 1
	v_cndmask_b32_e64 v37, v73, v76, s[0:1]
	v_mul_f32_e32 v73, 0x37800000, v37
	v_cndmask_b32_e32 v37, v37, v73, vcc
	v_cmp_class_f32_e32 vcc, v36, v69
	s_nop 1
	v_cndmask_b32_e32 v36, v37, v36, vcc
	v_div_scale_f32 v37, s[0:1], v36, v36, 1.0
	v_rcp_f32_e32 v73, v37
	s_nop 0
	v_fma_f32 v76, -v37, v73, 1.0
	v_fmac_f32_e32 v73, v76, v73
	v_div_scale_f32 v76, vcc, 1.0, v36, 1.0
	v_mul_f32_e32 v77, v76, v73
	v_fma_f32 v80, -v37, v77, v76
	v_fmac_f32_e32 v77, v80, v73
	v_fma_f32 v37, -v37, v77, v76
	v_div_fmas_f32 v37, v37, v73, v77
	v_div_fixup_f32 v76, v37, v36, 1.0
	v_mov_b32_e32 v36, v38
	v_mov_b32_e32 v37, v32
	v_mov_b32_e32 v32, v39
	v_pk_mul_f32 v[36:37], v[76:77], v[36:37] op_sel_hi:[0,1]
	v_pk_mul_f32 v[38:39], v[76:77], v[32:33] op_sel_hi:[0,1]
	s_mov_b64 s[14:15], 0x400
	v_lshl_add_u64 v[80:81], s[14:15], 2, v[60:61]
	v_pk_mul_f32 v[38:39], v[22:23], v[38:39]
	v_pk_mul_f32 v[36:37], v[20:21], v[36:37]
	global_store_dwordx4 v[80:81], v[36:39], off
	v_mov_b32_e32 v73, v59
	s_nop 0
	v_mov_b32_e32 v36, v78
	v_mov_b32_e32 v37, v34
	v_mov_b32_e32 v34, v79
	v_pk_mul_f32 v[36:37], v[76:77], v[36:37] op_sel_hi:[0,1]
	v_pk_mul_f32 v[38:39], v[76:77], v[34:35] op_sel_hi:[0,1]
	v_pk_mul_f32 v[38:39], v[18:19], v[38:39]
	v_pk_mul_f32 v[36:37], v[16:17], v[36:37]
	global_store_dwordx4 v[80:81], v[36:39], off offset:16
	s_nop 0
	s_nop 0
	v_pk_mul_f32 v[36:37], v[70:71], v[76:77] op_sel_hi:[1,0]
	v_pk_mul_f32 v[38:39], v[84:85], v[76:77] op_sel_hi:[1,0]
	v_pk_mul_f32 v[36:37], v[28:29], v[36:37]
	v_pk_mul_f32 v[38:39], v[30:31], v[38:39]
	global_store_dwordx4 v[80:81], v[36:39], off offset:2048
	s_nop 0
	s_nop 0
	v_pk_mul_f32 v[36:37], v[72:73], v[76:77] op_sel_hi:[1,0]
	v_pk_mul_f32 v[38:39], v[74:75], v[76:77] op_sel_hi:[1,0]
	v_pk_mul_f32 v[36:37], v[24:25], v[36:37]
	v_pk_mul_f32 v[38:39], v[26:27], v[38:39]
	global_store_dwordx4 v[80:81], v[36:39], off offset:2064
	s_nop 1
	s_nop 0
	s_nop 0
	s_nop 0
	s_nop 0
	s_waitcnt vmcnt(18)
	v_lshlrev_b32_e32 v72, 16, v182
	v_and_b32_e32 v59, 0xffff0000, v182
	v_lshlrev_b32_e32 v74, 16, v183
	v_and_b32_e32 v75, 0xffff0000, v183
	v_lshlrev_b32_e32 v183, 16, v177
	v_lshlrev_b32_e32 v182, 16, v176
	v_and_b32_e32 v177, 0xffff0000, v177
	v_and_b32_e32 v176, 0xffff0000, v176
	v_lshlrev_b32_e32 v79, 16, v179
	v_lshlrev_b32_e32 v78, 16, v178
	v_and_b32_e32 v179, 0xffff0000, v179
	v_and_b32_e32 v178, 0xffff0000, v178
	v_lshlrev_b32_e32 v70, 16, v180
	v_and_b32_e32 v71, 0xffff0000, v180
	v_pk_mul_f32 v[76:77], v[176:177], v[176:177]
	v_pk_mul_f32 v[80:81], v[178:179], v[178:179]
	v_lshlrev_b32_e32 v84, 16, v181
	v_pk_fma_f32 v[76:77], v[182:183], v[182:183], v[76:77]
	v_pk_fma_f32 v[80:81], v[78:79], v[78:79], v[80:81]
	v_mul_f32_e32 v73, v70, v70
	v_mul_f32_e32 v83, v71, v71
	v_and_b32_e32 v85, 0xffff0000, v181
	v_mul_f32_e32 v180, v84, v84
	v_mov_b32_e32 v82, v72
	v_pk_add_f32 v[76:77], v[76:77], v[76:77] op_sel_hi:[0,1]
	v_pk_add_f32 v[80:81], v[80:81], v[80:81] op_sel_hi:[0,1]
	v_pk_fma_f32 v[180:181], v[84:85], v[84:85], v[180:181] op_sel_hi:[1,1,0]
	v_pk_add_f32 v[82:83], v[72:73], v[82:83]
	v_mul_f32_e32 v180, v59, v59
	v_mul_f32_e32 v76, v74, v74
	v_mul_f32_e32 v80, v75, v75
	v_mul_f32_e32 v86, v72, v72
	v_mov_b32_e32 v87, v83
	v_pk_add_f32 v[180:181], v[86:87], v[180:181]
	v_pk_add_f32 v[76:77], v[76:77], v[80:81]
	v_pk_add_f32 v[180:181], v[180:181], v[76:77]
	v_add_f32_e32 v180, v180, v181
	s_nop 1
	v_add_f32_dpp v180, v180, v180 quad_perm:[1,0,3,2] row_mask:0xf bank_mask:0xf
	s_nop 1
	v_add_f32_dpp v180, v180, v180 quad_perm:[2,3,0,1] row_mask:0xf bank_mask:0xf
	s_nop 1
	v_add_f32_dpp v180, v180, v180 row_half_mirror row_mask:0xf bank_mask:0xf
	s_nop 1
	v_add_f32_dpp v180, v180, v180 row_ror:8 row_mask:0xf bank_mask:0xf
	v_mov_b32_e32 v181, v180
	s_nop 1
	v_permlane16_swap_b32_e32 v181, v180
	v_add_f32_e32 v180, v180, v181
	v_mov_b32_e32 v181, v180
	s_nop 1
	v_permlane32_swap_b32_e32 v181, v180
	v_add_f32_e32 v180, v180, v181
	v_fmamk_f32 v180, v180, 0x3a800000, v68
	v_mul_f32_e32 v181, 0x4f800000, v180
	v_cmp_gt_f32_e32 vcc, s3, v180
	s_nop 1
	v_cndmask_b32_e32 v180, v180, v181, vcc
	v_sqrt_f32_e32 v181, v180
	s_nop 0
	v_add_u32_e32 v73, -1, v181
	v_fma_f32 v76, -v73, v181, v180
	v_cmp_ge_f32_e64 s[0:1], 0, v76
	v_add_u32_e32 v76, 1, v181
	s_nop 0
	v_cndmask_b32_e64 v73, v181, v73, s[0:1]
	v_fma_f32 v181, -v76, v181, v180
	v_cmp_lt_f32_e64 s[0:1], 0, v181
	s_nop 1
	v_cndmask_b32_e64 v181, v73, v76, s[0:1]
	v_mul_f32_e32 v73, 0x37800000, v181
	v_cndmask_b32_e32 v181, v181, v73, vcc
	v_cmp_class_f32_e32 vcc, v180, v69
	s_nop 1
	v_cndmask_b32_e32 v180, v181, v180, vcc
	v_div_scale_f32 v181, s[0:1], v180, v180, 1.0
	v_rcp_f32_e32 v73, v181
	s_nop 0
	v_fma_f32 v76, -v181, v73, 1.0
	v_fmac_f32_e32 v73, v76, v73
	v_div_scale_f32 v76, vcc, 1.0, v180, 1.0
	v_mul_f32_e32 v77, v76, v73
	v_fma_f32 v80, -v181, v77, v76
	v_fmac_f32_e32 v77, v80, v73
	v_fma_f32 v181, -v181, v77, v76
	v_div_fmas_f32 v181, v181, v73, v77
	v_div_fixup_f32 v76, v181, v180, 1.0
	v_mov_b32_e32 v180, v182
	v_mov_b32_e32 v181, v176
	v_mov_b32_e32 v176, v183
	v_pk_mul_f32 v[180:181], v[76:77], v[180:181] op_sel_hi:[0,1]
	v_pk_mul_f32 v[182:183], v[76:77], v[176:177] op_sel_hi:[0,1]
	s_mov_b64 s[14:15], 0x800
	v_lshl_add_u64 v[80:81], s[14:15], 2, v[60:61]
	v_pk_mul_f32 v[182:183], v[22:23], v[182:183]
	v_pk_mul_f32 v[180:181], v[20:21], v[180:181]
	global_store_dwordx4 v[80:81], v[180:183], off
	v_mov_b32_e32 v73, v59
	s_nop 0
	v_mov_b32_e32 v180, v78
	v_mov_b32_e32 v181, v178
	v_mov_b32_e32 v178, v79
	v_pk_mul_f32 v[180:181], v[76:77], v[180:181] op_sel_hi:[0,1]
	v_pk_mul_f32 v[182:183], v[76:77], v[178:179] op_sel_hi:[0,1]
	v_pk_mul_f32 v[182:183], v[18:19], v[182:183]
	v_pk_mul_f32 v[180:181], v[16:17], v[180:181]
	global_store_dwordx4 v[80:81], v[180:183], off offset:16
	s_nop 0
	s_nop 0
	v_pk_mul_f32 v[180:181], v[70:71], v[76:77] op_sel_hi:[1,0]
	v_pk_mul_f32 v[182:183], v[84:85], v[76:77] op_sel_hi:[1,0]
	v_pk_mul_f32 v[180:181], v[28:29], v[180:181]
	v_pk_mul_f32 v[182:183], v[30:31], v[182:183]
	global_store_dwordx4 v[80:81], v[180:183], off offset:2048
	s_nop 0
	s_nop 0
	v_pk_mul_f32 v[180:181], v[72:73], v[76:77] op_sel_hi:[1,0]
	v_pk_mul_f32 v[182:183], v[74:75], v[76:77] op_sel_hi:[1,0]
	v_pk_mul_f32 v[180:181], v[24:25], v[180:181]
	v_pk_mul_f32 v[182:183], v[26:27], v[182:183]
	global_store_dwordx4 v[80:81], v[180:183], off offset:2064
	s_nop 1
	s_nop 0
	s_nop 0
	s_nop 0
	s_nop 0
	s_waitcnt vmcnt(20)
	v_lshlrev_b32_e32 v72, 16, v190
	v_and_b32_e32 v59, 0xffff0000, v190
	v_lshlrev_b32_e32 v74, 16, v191
	v_and_b32_e32 v75, 0xffff0000, v191
	v_lshlrev_b32_e32 v191, 16, v185
	v_lshlrev_b32_e32 v190, 16, v184
	v_and_b32_e32 v185, 0xffff0000, v185
	v_and_b32_e32 v184, 0xffff0000, v184
	v_lshlrev_b32_e32 v79, 16, v187
	v_lshlrev_b32_e32 v78, 16, v186
	v_and_b32_e32 v187, 0xffff0000, v187
	v_and_b32_e32 v186, 0xffff0000, v186
	v_lshlrev_b32_e32 v70, 16, v188
	v_and_b32_e32 v71, 0xffff0000, v188
	v_pk_mul_f32 v[76:77], v[184:185], v[184:185]
	v_pk_mul_f32 v[80:81], v[186:187], v[186:187]
	v_lshlrev_b32_e32 v84, 16, v189
	v_pk_fma_f32 v[76:77], v[190:191], v[190:191], v[76:77]
	v_pk_fma_f32 v[80:81], v[78:79], v[78:79], v[80:81]
	v_mul_f32_e32 v73, v70, v70
	v_mul_f32_e32 v83, v71, v71
	v_and_b32_e32 v85, 0xffff0000, v189
	v_mul_f32_e32 v188, v84, v84
	v_mov_b32_e32 v82, v72
	v_pk_add_f32 v[76:77], v[76:77], v[76:77] op_sel_hi:[0,1]
	v_pk_add_f32 v[80:81], v[80:81], v[80:81] op_sel_hi:[0,1]
	v_pk_fma_f32 v[188:189], v[84:85], v[84:85], v[188:189] op_sel_hi:[1,1,0]
	v_pk_add_f32 v[82:83], v[72:73], v[82:83]
	v_mul_f32_e32 v188, v59, v59
	v_mul_f32_e32 v76, v74, v74
	v_mul_f32_e32 v80, v75, v75
	v_mul_f32_e32 v86, v72, v72
	v_mov_b32_e32 v87, v83
	v_pk_add_f32 v[188:189], v[86:87], v[188:189]
	v_pk_add_f32 v[76:77], v[76:77], v[80:81]
	v_pk_add_f32 v[188:189], v[188:189], v[76:77]
	v_add_f32_e32 v188, v188, v189
	s_nop 1
	v_add_f32_dpp v188, v188, v188 quad_perm:[1,0,3,2] row_mask:0xf bank_mask:0xf
	s_nop 1
	v_add_f32_dpp v188, v188, v188 quad_perm:[2,3,0,1] row_mask:0xf bank_mask:0xf
	s_nop 1
	v_add_f32_dpp v188, v188, v188 row_half_mirror row_mask:0xf bank_mask:0xf
	s_nop 1
	v_add_f32_dpp v188, v188, v188 row_ror:8 row_mask:0xf bank_mask:0xf
	v_mov_b32_e32 v189, v188
	s_nop 1
	v_permlane16_swap_b32_e32 v189, v188
	v_add_f32_e32 v188, v188, v189
	v_mov_b32_e32 v189, v188
	s_nop 1
	v_permlane32_swap_b32_e32 v189, v188
	v_add_f32_e32 v188, v188, v189
	v_fmamk_f32 v188, v188, 0x3a800000, v68
	v_mul_f32_e32 v189, 0x4f800000, v188
	v_cmp_gt_f32_e32 vcc, s3, v188
	s_nop 1
	v_cndmask_b32_e32 v188, v188, v189, vcc
	v_sqrt_f32_e32 v189, v188
	s_nop 0
	v_add_u32_e32 v73, -1, v189
	v_fma_f32 v76, -v73, v189, v188
	v_cmp_ge_f32_e64 s[0:1], 0, v76
	v_add_u32_e32 v76, 1, v189
	s_nop 0
	v_cndmask_b32_e64 v73, v189, v73, s[0:1]
	v_fma_f32 v189, -v76, v189, v188
	v_cmp_lt_f32_e64 s[0:1], 0, v189
	s_nop 1
	v_cndmask_b32_e64 v189, v73, v76, s[0:1]
	v_mul_f32_e32 v73, 0x37800000, v189
	v_cndmask_b32_e32 v189, v189, v73, vcc
	v_cmp_class_f32_e32 vcc, v188, v69
	s_nop 1
	v_cndmask_b32_e32 v188, v189, v188, vcc
	v_div_scale_f32 v189, s[0:1], v188, v188, 1.0
	v_rcp_f32_e32 v73, v189
	s_nop 0
	v_fma_f32 v76, -v189, v73, 1.0
	v_fmac_f32_e32 v73, v76, v73
	v_div_scale_f32 v76, vcc, 1.0, v188, 1.0
	v_mul_f32_e32 v77, v76, v73
	v_fma_f32 v80, -v189, v77, v76
	v_fmac_f32_e32 v77, v80, v73
	v_fma_f32 v189, -v189, v77, v76
	v_div_fmas_f32 v189, v189, v73, v77
	v_div_fixup_f32 v76, v189, v188, 1.0
	v_mov_b32_e32 v188, v190
	v_mov_b32_e32 v189, v184
	v_mov_b32_e32 v184, v191
	v_pk_mul_f32 v[188:189], v[76:77], v[188:189] op_sel_hi:[0,1]
	v_pk_mul_f32 v[190:191], v[76:77], v[184:185] op_sel_hi:[0,1]
	s_mov_b64 s[14:15], 0xc00
	v_lshl_add_u64 v[80:81], s[14:15], 2, v[60:61]
	v_pk_mul_f32 v[190:191], v[22:23], v[190:191]
	v_pk_mul_f32 v[188:189], v[20:21], v[188:189]
	global_store_dwordx4 v[80:81], v[188:191], off
	v_mov_b32_e32 v73, v59
	s_nop 0
	v_mov_b32_e32 v188, v78
	v_mov_b32_e32 v189, v186
	v_mov_b32_e32 v186, v79
	v_pk_mul_f32 v[188:189], v[76:77], v[188:189] op_sel_hi:[0,1]
	v_pk_mul_f32 v[190:191], v[76:77], v[186:187] op_sel_hi:[0,1]
	v_pk_mul_f32 v[190:191], v[18:19], v[190:191]
	v_pk_mul_f32 v[188:189], v[16:17], v[188:189]
	global_store_dwordx4 v[80:81], v[188:191], off offset:16
	s_nop 0
	s_nop 0
	v_pk_mul_f32 v[188:189], v[70:71], v[76:77] op_sel_hi:[1,0]
	v_pk_mul_f32 v[190:191], v[84:85], v[76:77] op_sel_hi:[1,0]
	v_pk_mul_f32 v[188:189], v[28:29], v[188:189]
	v_pk_mul_f32 v[190:191], v[30:31], v[190:191]
	global_store_dwordx4 v[80:81], v[188:191], off offset:2048
	s_nop 0
	s_nop 0
	v_pk_mul_f32 v[188:189], v[72:73], v[76:77] op_sel_hi:[1,0]
	v_pk_mul_f32 v[190:191], v[74:75], v[76:77] op_sel_hi:[1,0]
	v_pk_mul_f32 v[188:189], v[24:25], v[188:189]
	v_pk_mul_f32 v[190:191], v[26:27], v[190:191]
	global_store_dwordx4 v[80:81], v[188:191], off offset:2064
	s_nop 1
	s_nop 0
	s_nop 0
	s_nop 0
	s_nop 0
	s_waitcnt vmcnt(22)
	v_lshlrev_b32_e32 v72, 16, v198
	v_and_b32_e32 v59, 0xffff0000, v198
	v_lshlrev_b32_e32 v74, 16, v199
	v_and_b32_e32 v75, 0xffff0000, v199
	v_lshlrev_b32_e32 v199, 16, v193
	v_lshlrev_b32_e32 v198, 16, v192
	v_and_b32_e32 v193, 0xffff0000, v193
	v_and_b32_e32 v192, 0xffff0000, v192
	v_lshlrev_b32_e32 v79, 16, v195
	v_lshlrev_b32_e32 v78, 16, v194
	v_and_b32_e32 v195, 0xffff0000, v195
	v_and_b32_e32 v194, 0xffff0000, v194
	v_lshlrev_b32_e32 v70, 16, v196
	v_and_b32_e32 v71, 0xffff0000, v196
	v_pk_mul_f32 v[76:77], v[192:193], v[192:193]
	v_pk_mul_f32 v[80:81], v[194:195], v[194:195]
	v_lshlrev_b32_e32 v84, 16, v197
	v_pk_fma_f32 v[76:77], v[198:199], v[198:199], v[76:77]
	v_pk_fma_f32 v[80:81], v[78:79], v[78:79], v[80:81]
	v_mul_f32_e32 v73, v70, v70
	v_mul_f32_e32 v83, v71, v71
	v_and_b32_e32 v85, 0xffff0000, v197
	v_mul_f32_e32 v196, v84, v84
	v_mov_b32_e32 v82, v72
	v_pk_add_f32 v[76:77], v[76:77], v[76:77] op_sel_hi:[0,1]
	v_pk_add_f32 v[80:81], v[80:81], v[80:81] op_sel_hi:[0,1]
	v_pk_fma_f32 v[196:197], v[84:85], v[84:85], v[196:197] op_sel_hi:[1,1,0]
	v_pk_add_f32 v[82:83], v[72:73], v[82:83]
	v_mul_f32_e32 v196, v59, v59
	v_mul_f32_e32 v76, v74, v74
	v_mul_f32_e32 v80, v75, v75
	v_mul_f32_e32 v86, v72, v72
	v_mov_b32_e32 v87, v83
	v_pk_add_f32 v[196:197], v[86:87], v[196:197]
	v_pk_add_f32 v[76:77], v[76:77], v[80:81]
	v_pk_add_f32 v[196:197], v[196:197], v[76:77]
	v_add_f32_e32 v196, v196, v197
	s_nop 1
	v_add_f32_dpp v196, v196, v196 quad_perm:[1,0,3,2] row_mask:0xf bank_mask:0xf
	s_nop 1
	v_add_f32_dpp v196, v196, v196 quad_perm:[2,3,0,1] row_mask:0xf bank_mask:0xf
	s_nop 1
	v_add_f32_dpp v196, v196, v196 row_half_mirror row_mask:0xf bank_mask:0xf
	s_nop 1
	v_add_f32_dpp v196, v196, v196 row_ror:8 row_mask:0xf bank_mask:0xf
	v_mov_b32_e32 v197, v196
	s_nop 1
	v_permlane16_swap_b32_e32 v197, v196
	v_add_f32_e32 v196, v196, v197
	v_mov_b32_e32 v197, v196
	s_nop 1
	v_permlane32_swap_b32_e32 v197, v196
	v_add_f32_e32 v196, v196, v197
	v_fmamk_f32 v196, v196, 0x3a800000, v68
	v_mul_f32_e32 v197, 0x4f800000, v196
	v_cmp_gt_f32_e32 vcc, s3, v196
	s_nop 1
	v_cndmask_b32_e32 v196, v196, v197, vcc
	v_sqrt_f32_e32 v197, v196
	s_nop 0
	v_add_u32_e32 v73, -1, v197
	v_fma_f32 v76, -v73, v197, v196
	v_cmp_ge_f32_e64 s[0:1], 0, v76
	v_add_u32_e32 v76, 1, v197
	s_nop 0
	v_cndmask_b32_e64 v73, v197, v73, s[0:1]
	v_fma_f32 v197, -v76, v197, v196
	v_cmp_lt_f32_e64 s[0:1], 0, v197
	s_nop 1
	v_cndmask_b32_e64 v197, v73, v76, s[0:1]
	v_mul_f32_e32 v73, 0x37800000, v197
	v_cndmask_b32_e32 v197, v197, v73, vcc
	v_cmp_class_f32_e32 vcc, v196, v69
	s_nop 1
	v_cndmask_b32_e32 v196, v197, v196, vcc
	v_div_scale_f32 v197, s[0:1], v196, v196, 1.0
	v_rcp_f32_e32 v73, v197
	s_nop 0
	v_fma_f32 v76, -v197, v73, 1.0
	v_fmac_f32_e32 v73, v76, v73
	v_div_scale_f32 v76, vcc, 1.0, v196, 1.0
	v_mul_f32_e32 v77, v76, v73
	v_fma_f32 v80, -v197, v77, v76
	v_fmac_f32_e32 v77, v80, v73
	v_fma_f32 v197, -v197, v77, v76
	v_div_fmas_f32 v197, v197, v73, v77
	v_div_fixup_f32 v76, v197, v196, 1.0
	v_mov_b32_e32 v196, v198
	v_mov_b32_e32 v197, v192
	v_mov_b32_e32 v192, v199
	v_pk_mul_f32 v[196:197], v[76:77], v[196:197] op_sel_hi:[0,1]
	v_pk_mul_f32 v[198:199], v[76:77], v[192:193] op_sel_hi:[0,1]
	s_mov_b64 s[14:15], 0x1000
	v_lshl_add_u64 v[80:81], s[14:15], 2, v[60:61]
	v_pk_mul_f32 v[198:199], v[22:23], v[198:199]
	v_pk_mul_f32 v[196:197], v[20:21], v[196:197]
	global_store_dwordx4 v[80:81], v[196:199], off
	v_mov_b32_e32 v73, v59
	s_nop 0
	v_mov_b32_e32 v196, v78
	v_mov_b32_e32 v197, v194
	v_mov_b32_e32 v194, v79
	v_pk_mul_f32 v[196:197], v[76:77], v[196:197] op_sel_hi:[0,1]
	v_pk_mul_f32 v[198:199], v[76:77], v[194:195] op_sel_hi:[0,1]
	v_pk_mul_f32 v[198:199], v[18:19], v[198:199]
	v_pk_mul_f32 v[196:197], v[16:17], v[196:197]
	global_store_dwordx4 v[80:81], v[196:199], off offset:16
	s_nop 0
	s_nop 0
	v_pk_mul_f32 v[196:197], v[70:71], v[76:77] op_sel_hi:[1,0]
	v_pk_mul_f32 v[198:199], v[84:85], v[76:77] op_sel_hi:[1,0]
	v_pk_mul_f32 v[196:197], v[28:29], v[196:197]
	v_pk_mul_f32 v[198:199], v[30:31], v[198:199]
	global_store_dwordx4 v[80:81], v[196:199], off offset:2048
	s_nop 0
	s_nop 0
	v_pk_mul_f32 v[196:197], v[72:73], v[76:77] op_sel_hi:[1,0]
	v_pk_mul_f32 v[198:199], v[74:75], v[76:77] op_sel_hi:[1,0]
	v_pk_mul_f32 v[196:197], v[24:25], v[196:197]
	v_pk_mul_f32 v[198:199], v[26:27], v[198:199]
	global_store_dwordx4 v[80:81], v[196:199], off offset:2064
	s_nop 1
	s_nop 0
	s_nop 0
	s_nop 0
	s_nop 0
	s_waitcnt vmcnt(24)
	v_lshlrev_b32_e32 v72, 16, v206
	v_and_b32_e32 v59, 0xffff0000, v206
	v_lshlrev_b32_e32 v74, 16, v207
	v_and_b32_e32 v75, 0xffff0000, v207
	v_lshlrev_b32_e32 v207, 16, v201
	v_lshlrev_b32_e32 v206, 16, v200
	v_and_b32_e32 v201, 0xffff0000, v201
	v_and_b32_e32 v200, 0xffff0000, v200
	v_lshlrev_b32_e32 v79, 16, v203
	v_lshlrev_b32_e32 v78, 16, v202
	v_and_b32_e32 v203, 0xffff0000, v203
	v_and_b32_e32 v202, 0xffff0000, v202
	v_lshlrev_b32_e32 v70, 16, v204
	v_and_b32_e32 v71, 0xffff0000, v204
	v_pk_mul_f32 v[76:77], v[200:201], v[200:201]
	v_pk_mul_f32 v[80:81], v[202:203], v[202:203]
	v_lshlrev_b32_e32 v84, 16, v205
	v_pk_fma_f32 v[76:77], v[206:207], v[206:207], v[76:77]
	v_pk_fma_f32 v[80:81], v[78:79], v[78:79], v[80:81]
	v_mul_f32_e32 v73, v70, v70
	v_mul_f32_e32 v83, v71, v71
	v_and_b32_e32 v85, 0xffff0000, v205
	v_mul_f32_e32 v204, v84, v84
	v_mov_b32_e32 v82, v72
	v_pk_add_f32 v[76:77], v[76:77], v[76:77] op_sel_hi:[0,1]
	v_pk_add_f32 v[80:81], v[80:81], v[80:81] op_sel_hi:[0,1]
	v_pk_fma_f32 v[204:205], v[84:85], v[84:85], v[204:205] op_sel_hi:[1,1,0]
	v_pk_add_f32 v[82:83], v[72:73], v[82:83]
	v_mul_f32_e32 v204, v59, v59
	v_mul_f32_e32 v76, v74, v74
	v_mul_f32_e32 v80, v75, v75
	v_mul_f32_e32 v86, v72, v72
	v_mov_b32_e32 v87, v83
	v_pk_add_f32 v[204:205], v[86:87], v[204:205]
	v_pk_add_f32 v[76:77], v[76:77], v[80:81]
	v_pk_add_f32 v[204:205], v[204:205], v[76:77]
	v_add_f32_e32 v204, v204, v205
	s_nop 1
	v_add_f32_dpp v204, v204, v204 quad_perm:[1,0,3,2] row_mask:0xf bank_mask:0xf
	s_nop 1
	v_add_f32_dpp v204, v204, v204 quad_perm:[2,3,0,1] row_mask:0xf bank_mask:0xf
	s_nop 1
	v_add_f32_dpp v204, v204, v204 row_half_mirror row_mask:0xf bank_mask:0xf
	s_nop 1
	v_add_f32_dpp v204, v204, v204 row_ror:8 row_mask:0xf bank_mask:0xf
	v_mov_b32_e32 v205, v204
	s_nop 1
	v_permlane16_swap_b32_e32 v205, v204
	v_add_f32_e32 v204, v204, v205
	v_mov_b32_e32 v205, v204
	s_nop 1
	v_permlane32_swap_b32_e32 v205, v204
	v_add_f32_e32 v204, v204, v205
	v_fmamk_f32 v204, v204, 0x3a800000, v68
	v_mul_f32_e32 v205, 0x4f800000, v204
	v_cmp_gt_f32_e32 vcc, s3, v204
	s_nop 1
	v_cndmask_b32_e32 v204, v204, v205, vcc
	v_sqrt_f32_e32 v205, v204
	s_nop 0
	v_add_u32_e32 v73, -1, v205
	v_fma_f32 v76, -v73, v205, v204
	v_cmp_ge_f32_e64 s[0:1], 0, v76
	v_add_u32_e32 v76, 1, v205
	s_nop 0
	v_cndmask_b32_e64 v73, v205, v73, s[0:1]
	v_fma_f32 v205, -v76, v205, v204
	v_cmp_lt_f32_e64 s[0:1], 0, v205
	s_nop 1
	v_cndmask_b32_e64 v205, v73, v76, s[0:1]
	v_mul_f32_e32 v73, 0x37800000, v205
	v_cndmask_b32_e32 v205, v205, v73, vcc
	v_cmp_class_f32_e32 vcc, v204, v69
	s_nop 1
	v_cndmask_b32_e32 v204, v205, v204, vcc
	v_div_scale_f32 v205, s[0:1], v204, v204, 1.0
	v_rcp_f32_e32 v73, v205
	s_nop 0
	v_fma_f32 v76, -v205, v73, 1.0
	v_fmac_f32_e32 v73, v76, v73
	v_div_scale_f32 v76, vcc, 1.0, v204, 1.0
	v_mul_f32_e32 v77, v76, v73
	v_fma_f32 v80, -v205, v77, v76
	v_fmac_f32_e32 v77, v80, v73
	v_fma_f32 v205, -v205, v77, v76
	v_div_fmas_f32 v205, v205, v73, v77
	v_div_fixup_f32 v76, v205, v204, 1.0
	v_mov_b32_e32 v204, v206
	v_mov_b32_e32 v205, v200
	v_mov_b32_e32 v200, v207
	v_pk_mul_f32 v[204:205], v[76:77], v[204:205] op_sel_hi:[0,1]
	v_pk_mul_f32 v[206:207], v[76:77], v[200:201] op_sel_hi:[0,1]
	s_mov_b64 s[14:15], 0x1400
	v_lshl_add_u64 v[80:81], s[14:15], 2, v[60:61]
	v_pk_mul_f32 v[206:207], v[22:23], v[206:207]
	v_pk_mul_f32 v[204:205], v[20:21], v[204:205]
	global_store_dwordx4 v[80:81], v[204:207], off
	v_mov_b32_e32 v73, v59
	s_nop 0
	v_mov_b32_e32 v204, v78
	v_mov_b32_e32 v205, v202
	v_mov_b32_e32 v202, v79
	v_pk_mul_f32 v[204:205], v[76:77], v[204:205] op_sel_hi:[0,1]
	v_pk_mul_f32 v[206:207], v[76:77], v[202:203] op_sel_hi:[0,1]
	v_pk_mul_f32 v[206:207], v[18:19], v[206:207]
	v_pk_mul_f32 v[204:205], v[16:17], v[204:205]
	global_store_dwordx4 v[80:81], v[204:207], off offset:16
	s_nop 0
	s_nop 0
	v_pk_mul_f32 v[204:205], v[70:71], v[76:77] op_sel_hi:[1,0]
	v_pk_mul_f32 v[206:207], v[84:85], v[76:77] op_sel_hi:[1,0]
	v_pk_mul_f32 v[204:205], v[28:29], v[204:205]
	v_pk_mul_f32 v[206:207], v[30:31], v[206:207]
	global_store_dwordx4 v[80:81], v[204:207], off offset:2048
	s_nop 0
	s_nop 0
	v_pk_mul_f32 v[204:205], v[72:73], v[76:77] op_sel_hi:[1,0]
	v_pk_mul_f32 v[206:207], v[74:75], v[76:77] op_sel_hi:[1,0]
	v_pk_mul_f32 v[204:205], v[24:25], v[204:205]
	v_pk_mul_f32 v[206:207], v[26:27], v[206:207]
	global_store_dwordx4 v[80:81], v[204:207], off offset:2064
	s_nop 1
	s_nop 0
	s_nop 0
	s_nop 0
	s_nop 0
	s_waitcnt vmcnt(26)
	v_lshlrev_b32_e32 v72, 16, v214
	v_and_b32_e32 v59, 0xffff0000, v214
	v_lshlrev_b32_e32 v74, 16, v215
	v_and_b32_e32 v75, 0xffff0000, v215
	v_lshlrev_b32_e32 v215, 16, v209
	v_lshlrev_b32_e32 v214, 16, v208
	v_and_b32_e32 v209, 0xffff0000, v209
	v_and_b32_e32 v208, 0xffff0000, v208
	v_lshlrev_b32_e32 v79, 16, v211
	v_lshlrev_b32_e32 v78, 16, v210
	v_and_b32_e32 v211, 0xffff0000, v211
	v_and_b32_e32 v210, 0xffff0000, v210
	v_lshlrev_b32_e32 v70, 16, v212
	v_and_b32_e32 v71, 0xffff0000, v212
	v_pk_mul_f32 v[76:77], v[208:209], v[208:209]
	v_pk_mul_f32 v[80:81], v[210:211], v[210:211]
	v_lshlrev_b32_e32 v84, 16, v213
	v_pk_fma_f32 v[76:77], v[214:215], v[214:215], v[76:77]
	v_pk_fma_f32 v[80:81], v[78:79], v[78:79], v[80:81]
	v_mul_f32_e32 v73, v70, v70
	v_mul_f32_e32 v83, v71, v71
	v_and_b32_e32 v85, 0xffff0000, v213
	v_mul_f32_e32 v212, v84, v84
	v_mov_b32_e32 v82, v72
	v_pk_add_f32 v[76:77], v[76:77], v[76:77] op_sel_hi:[0,1]
	v_pk_add_f32 v[80:81], v[80:81], v[80:81] op_sel_hi:[0,1]
	v_pk_fma_f32 v[212:213], v[84:85], v[84:85], v[212:213] op_sel_hi:[1,1,0]
	v_pk_add_f32 v[82:83], v[72:73], v[82:83]
	v_mul_f32_e32 v212, v59, v59
	v_mul_f32_e32 v76, v74, v74
	v_mul_f32_e32 v80, v75, v75
	v_mul_f32_e32 v86, v72, v72
	v_mov_b32_e32 v87, v83
	v_pk_add_f32 v[212:213], v[86:87], v[212:213]
	v_pk_add_f32 v[76:77], v[76:77], v[80:81]
	v_pk_add_f32 v[212:213], v[212:213], v[76:77]
	v_add_f32_e32 v212, v212, v213
	s_nop 1
	v_add_f32_dpp v212, v212, v212 quad_perm:[1,0,3,2] row_mask:0xf bank_mask:0xf
	s_nop 1
	v_add_f32_dpp v212, v212, v212 quad_perm:[2,3,0,1] row_mask:0xf bank_mask:0xf
	s_nop 1
	v_add_f32_dpp v212, v212, v212 row_half_mirror row_mask:0xf bank_mask:0xf
	s_nop 1
	v_add_f32_dpp v212, v212, v212 row_ror:8 row_mask:0xf bank_mask:0xf
	v_mov_b32_e32 v213, v212
	s_nop 1
	v_permlane16_swap_b32_e32 v213, v212
	v_add_f32_e32 v212, v212, v213
	v_mov_b32_e32 v213, v212
	s_nop 1
	v_permlane32_swap_b32_e32 v213, v212
	v_add_f32_e32 v212, v212, v213
	v_fmamk_f32 v212, v212, 0x3a800000, v68
	v_mul_f32_e32 v213, 0x4f800000, v212
	v_cmp_gt_f32_e32 vcc, s3, v212
	s_nop 1
	v_cndmask_b32_e32 v212, v212, v213, vcc
	v_sqrt_f32_e32 v213, v212
	s_nop 0
	v_add_u32_e32 v73, -1, v213
	v_fma_f32 v76, -v73, v213, v212
	v_cmp_ge_f32_e64 s[0:1], 0, v76
	v_add_u32_e32 v76, 1, v213
	s_nop 0
	v_cndmask_b32_e64 v73, v213, v73, s[0:1]
	v_fma_f32 v213, -v76, v213, v212
	v_cmp_lt_f32_e64 s[0:1], 0, v213
	s_nop 1
	v_cndmask_b32_e64 v213, v73, v76, s[0:1]
	v_mul_f32_e32 v73, 0x37800000, v213
	v_cndmask_b32_e32 v213, v213, v73, vcc
	v_cmp_class_f32_e32 vcc, v212, v69
	s_nop 1
	v_cndmask_b32_e32 v212, v213, v212, vcc
	v_div_scale_f32 v213, s[0:1], v212, v212, 1.0
	v_rcp_f32_e32 v73, v213
	s_nop 0
	v_fma_f32 v76, -v213, v73, 1.0
	v_fmac_f32_e32 v73, v76, v73
	v_div_scale_f32 v76, vcc, 1.0, v212, 1.0
	v_mul_f32_e32 v77, v76, v73
	v_fma_f32 v80, -v213, v77, v76
	v_fmac_f32_e32 v77, v80, v73
	v_fma_f32 v213, -v213, v77, v76
	v_div_fmas_f32 v213, v213, v73, v77
	v_div_fixup_f32 v76, v213, v212, 1.0
	v_mov_b32_e32 v212, v214
	v_mov_b32_e32 v213, v208
	v_mov_b32_e32 v208, v215
	v_pk_mul_f32 v[212:213], v[76:77], v[212:213] op_sel_hi:[0,1]
	v_pk_mul_f32 v[214:215], v[76:77], v[208:209] op_sel_hi:[0,1]
	s_mov_b64 s[14:15], 0x1800
	v_lshl_add_u64 v[80:81], s[14:15], 2, v[60:61]
	v_pk_mul_f32 v[214:215], v[22:23], v[214:215]
	v_pk_mul_f32 v[212:213], v[20:21], v[212:213]
	global_store_dwordx4 v[80:81], v[212:215], off
	v_mov_b32_e32 v73, v59
	s_nop 0
	v_mov_b32_e32 v212, v78
	v_mov_b32_e32 v213, v210
	v_mov_b32_e32 v210, v79
	v_pk_mul_f32 v[212:213], v[76:77], v[212:213] op_sel_hi:[0,1]
	v_pk_mul_f32 v[214:215], v[76:77], v[210:211] op_sel_hi:[0,1]
	v_pk_mul_f32 v[214:215], v[18:19], v[214:215]
	v_pk_mul_f32 v[212:213], v[16:17], v[212:213]
	global_store_dwordx4 v[80:81], v[212:215], off offset:16
	s_nop 0
	s_nop 0
	v_pk_mul_f32 v[212:213], v[70:71], v[76:77] op_sel_hi:[1,0]
	v_pk_mul_f32 v[214:215], v[84:85], v[76:77] op_sel_hi:[1,0]
	v_pk_mul_f32 v[212:213], v[28:29], v[212:213]
	v_pk_mul_f32 v[214:215], v[30:31], v[214:215]
	global_store_dwordx4 v[80:81], v[212:215], off offset:2048
	s_nop 0
	s_nop 0
	v_pk_mul_f32 v[212:213], v[72:73], v[76:77] op_sel_hi:[1,0]
	v_pk_mul_f32 v[214:215], v[74:75], v[76:77] op_sel_hi:[1,0]
	v_pk_mul_f32 v[212:213], v[24:25], v[212:213]
	v_pk_mul_f32 v[214:215], v[26:27], v[214:215]
	global_store_dwordx4 v[80:81], v[212:215], off offset:2064
	s_nop 1
	s_nop 0
	s_nop 0
	s_nop 0
	s_nop 0
	s_waitcnt vmcnt(28)
	v_lshlrev_b32_e32 v72, 16, v222
	v_and_b32_e32 v59, 0xffff0000, v222
	v_lshlrev_b32_e32 v74, 16, v223
	v_and_b32_e32 v75, 0xffff0000, v223
	v_lshlrev_b32_e32 v223, 16, v217
	v_lshlrev_b32_e32 v222, 16, v216
	v_and_b32_e32 v217, 0xffff0000, v217
	v_and_b32_e32 v216, 0xffff0000, v216
	v_lshlrev_b32_e32 v79, 16, v219
	v_lshlrev_b32_e32 v78, 16, v218
	v_and_b32_e32 v219, 0xffff0000, v219
	v_and_b32_e32 v218, 0xffff0000, v218
	v_lshlrev_b32_e32 v70, 16, v220
	v_and_b32_e32 v71, 0xffff0000, v220
	v_pk_mul_f32 v[76:77], v[216:217], v[216:217]
	v_pk_mul_f32 v[80:81], v[218:219], v[218:219]
	v_lshlrev_b32_e32 v84, 16, v221
	v_pk_fma_f32 v[76:77], v[222:223], v[222:223], v[76:77]
	v_pk_fma_f32 v[80:81], v[78:79], v[78:79], v[80:81]
	v_mul_f32_e32 v73, v70, v70
	v_mul_f32_e32 v83, v71, v71
	v_and_b32_e32 v85, 0xffff0000, v221
	v_mul_f32_e32 v220, v84, v84
	v_mov_b32_e32 v82, v72
	v_pk_add_f32 v[76:77], v[76:77], v[76:77] op_sel_hi:[0,1]
	v_pk_add_f32 v[80:81], v[80:81], v[80:81] op_sel_hi:[0,1]
	v_pk_fma_f32 v[220:221], v[84:85], v[84:85], v[220:221] op_sel_hi:[1,1,0]
	v_pk_add_f32 v[82:83], v[72:73], v[82:83]
	v_mul_f32_e32 v220, v59, v59
	v_mul_f32_e32 v76, v74, v74
	v_mul_f32_e32 v80, v75, v75
	v_mul_f32_e32 v86, v72, v72
	v_mov_b32_e32 v87, v83
	v_pk_add_f32 v[220:221], v[86:87], v[220:221]
	v_pk_add_f32 v[76:77], v[76:77], v[80:81]
	v_pk_add_f32 v[220:221], v[220:221], v[76:77]
	v_add_f32_e32 v220, v220, v221
	s_nop 1
	v_add_f32_dpp v220, v220, v220 quad_perm:[1,0,3,2] row_mask:0xf bank_mask:0xf
	s_nop 1
	v_add_f32_dpp v220, v220, v220 quad_perm:[2,3,0,1] row_mask:0xf bank_mask:0xf
	s_nop 1
	v_add_f32_dpp v220, v220, v220 row_half_mirror row_mask:0xf bank_mask:0xf
	s_nop 1
	v_add_f32_dpp v220, v220, v220 row_ror:8 row_mask:0xf bank_mask:0xf
	v_mov_b32_e32 v221, v220
	s_nop 1
	v_permlane16_swap_b32_e32 v221, v220
	v_add_f32_e32 v220, v220, v221
	v_mov_b32_e32 v221, v220
	s_nop 1
	v_permlane32_swap_b32_e32 v221, v220
	v_add_f32_e32 v220, v220, v221
	v_fmamk_f32 v220, v220, 0x3a800000, v68
	v_mul_f32_e32 v221, 0x4f800000, v220
	v_cmp_gt_f32_e32 vcc, s3, v220
	s_nop 1
	v_cndmask_b32_e32 v220, v220, v221, vcc
	v_sqrt_f32_e32 v221, v220
	s_nop 0
	v_add_u32_e32 v73, -1, v221
	v_fma_f32 v76, -v73, v221, v220
	v_cmp_ge_f32_e64 s[0:1], 0, v76
	v_add_u32_e32 v76, 1, v221
	s_nop 0
	v_cndmask_b32_e64 v73, v221, v73, s[0:1]
	v_fma_f32 v221, -v76, v221, v220
	v_cmp_lt_f32_e64 s[0:1], 0, v221
	s_nop 1
	v_cndmask_b32_e64 v221, v73, v76, s[0:1]
	v_mul_f32_e32 v73, 0x37800000, v221
	v_cndmask_b32_e32 v221, v221, v73, vcc
	v_cmp_class_f32_e32 vcc, v220, v69
	s_nop 1
	v_cndmask_b32_e32 v220, v221, v220, vcc
	v_div_scale_f32 v221, s[0:1], v220, v220, 1.0
	v_rcp_f32_e32 v73, v221
	s_nop 0
	v_fma_f32 v76, -v221, v73, 1.0
	v_fmac_f32_e32 v73, v76, v73
	v_div_scale_f32 v76, vcc, 1.0, v220, 1.0
	v_mul_f32_e32 v77, v76, v73
	v_fma_f32 v80, -v221, v77, v76
	v_fmac_f32_e32 v77, v80, v73
	v_fma_f32 v221, -v221, v77, v76
	v_div_fmas_f32 v221, v221, v73, v77
	v_div_fixup_f32 v76, v221, v220, 1.0
	v_mov_b32_e32 v220, v222
	v_mov_b32_e32 v221, v216
	v_mov_b32_e32 v216, v223
	v_pk_mul_f32 v[220:221], v[76:77], v[220:221] op_sel_hi:[0,1]
	v_pk_mul_f32 v[222:223], v[76:77], v[216:217] op_sel_hi:[0,1]
	s_mov_b64 s[14:15], 0x1c00
	v_lshl_add_u64 v[80:81], s[14:15], 2, v[60:61]
	v_pk_mul_f32 v[222:223], v[22:23], v[222:223]
	v_pk_mul_f32 v[220:221], v[20:21], v[220:221]
	global_store_dwordx4 v[80:81], v[220:223], off
	v_mov_b32_e32 v73, v59
	s_nop 0
	v_mov_b32_e32 v220, v78
	v_mov_b32_e32 v221, v218
	v_mov_b32_e32 v218, v79
	v_pk_mul_f32 v[220:221], v[76:77], v[220:221] op_sel_hi:[0,1]
	v_pk_mul_f32 v[222:223], v[76:77], v[218:219] op_sel_hi:[0,1]
	v_pk_mul_f32 v[222:223], v[18:19], v[222:223]
	v_pk_mul_f32 v[220:221], v[16:17], v[220:221]
	global_store_dwordx4 v[80:81], v[220:223], off offset:16
	s_nop 0
	s_nop 0
	v_pk_mul_f32 v[220:221], v[70:71], v[76:77] op_sel_hi:[1,0]
	v_pk_mul_f32 v[222:223], v[84:85], v[76:77] op_sel_hi:[1,0]
	v_pk_mul_f32 v[220:221], v[28:29], v[220:221]
	v_pk_mul_f32 v[222:223], v[30:31], v[222:223]
	global_store_dwordx4 v[80:81], v[220:223], off offset:2048
	s_nop 0
	s_nop 0
	v_pk_mul_f32 v[220:221], v[72:73], v[76:77] op_sel_hi:[1,0]
	v_pk_mul_f32 v[222:223], v[74:75], v[76:77] op_sel_hi:[1,0]
	v_pk_mul_f32 v[220:221], v[24:25], v[220:221]
	v_pk_mul_f32 v[222:223], v[26:27], v[222:223]
	global_store_dwordx4 v[80:81], v[220:223], off offset:2064
	s_nop 1
	s_nop 0
	s_nop 0
	s_nop 0
	s_nop 0
	s_branch .LBB0_1389
